# speedup vs baseline: 1.0052x; 1.0052x over previous
; __device__ __forceinline__ float bf2f(u16 h) { return __uint_as_float(((unsigned)h) << 16); }
; __device__ __forceinline__ float sigmoidf_(float x) { return 1.f / (1.f + __expf(-x)); }
; template <int EPI>
; __device__ __forceinline__ void gemm_tile(const u16* __restrict__ A, long lda, const u16* __restrict__ Bt, long ldb, int K,
;                                           int brow, int bcol, const Epi& e, u16* shm) {
;     ...
;   for (int mh = 0; mh < 4; ++mh) {
;     float ta[4][2][4], tg[4][2][4];
; #pragma unroll
;     for (int m = mh; m < mh + 1; ++m)
; #pragma unroll
;     for (int n = 0; n < 2; ++n)
; #pragma unroll
;     for (int j = 0; j < 4; ++j) {
;       const int row = brow + ai * HALF + wr * 64 + m * 16 + fq * 4 + j, col = bcol + bj * HALF + wc * 32 + n * 16 + fr;
;       ta[m][n][j] = 0.f; tg[m][n][j] = 0.f;
;       if constexpr (EPI == EPI_RES) ta[m][n][j] = e.res[(long)row * D + col];
;       if constexpr (EPI == EPI_MRG1 || EPI == EPI_MRG2) ta[m][n][j] = e.cf[(long)row * D + col];
;       if constexpr (EPI == EPI_MRG0) tg[m][n][j] = bf2f(e.proj[(long)row * NC + OG + col]);
;       if constexpr (EPI == EPI_MRG1) tg[m][n][j] = bf2f(e.proj[(long)row * NC + OG + 2048 + col]);
;       if constexpr (EPI == EPI_MRG2) tg[m][n][j] = bf2f(e.proj[(long)row * NC + OG + 4096 + col]);
;     }
; #pragma unroll
;     for (int m = mh; m < mh + 1; ++m)
; #pragma unroll
;     for (int n = 0; n < 2; ++n)
; #pragma unroll
;     for (int j = 0; j < 4; ++j) {
;       const int row = brow + ai * HALF + wr * 64 + m * 16 + fq * 4 + j, col = bcol + bj * HALF + wc * 32 + n * 16 + fr;
;       const float v = acc[ai][bj][m][n][j];
;       if constexpr (EPI == EPI_RES) e.cf[(long)row * D + col] = ta[m][n][j] + v;
;       if constexpr (EPI == EPI_MRG0) e.cf[(long)row * D + col] = sigmoidf_(tg[m][n][j]) * v;
;       if constexpr (EPI == EPI_MRG1) e.cf[(long)row * D + col] = ta[m][n][j] + sigmoidf_(tg[m][n][j]) * v;
;       if constexpr (EPI == EPI_MRG2) e.cb[(long)row * D + col] = f2bf(ta[m][n][j] + sigmoidf_(tg[m][n][j]) * v);
;     }
.LBB0_1146:
	s_or_b64 exec, exec, s[0:1]
	v_mov_b32_e32 v0, v188
	s_mov_b64 s[0:1], 0x100000
	v_ashrrev_i32_e32 v2, 2, v0
	v_and_b32_e32 v2, 0xffffffc0, v2
	v_and_b32_e32 v1, 15, v0
	v_lshrrev_b32_e32 v136, 2, v0
	v_lshl_add_u32 v2, s18, 8, v2
	v_lshrrev_b32_e32 v0, 1, v0
	v_and_or_b32 v166, v136, 12, v2
	v_and_b32_e32 v0, 0x60, v0
	v_or3_b32 v144, v1, v0, s14
	v_or_b32_e32 v136, 1, v166
	v_ashrrev_i32_e32 v145, 31, v144
	v_ashrrev_i32_e32 v137, 31, v136
	v_lshlrev_b64 v[0:1], 2, v[144:145]
	v_ashrrev_i32_e32 v167, 31, v166
	v_lshlrev_b64 v[154:155], 13, v[136:137]
	v_or_b32_e32 v136, 2, v166
	v_lshl_add_u64 v[138:139], s[10:11], 0, v[0:1]
	v_lshlrev_b64 v[140:141], 13, v[166:167]
	v_ashrrev_i32_e32 v137, 31, v136
	v_lshl_add_u64 v[146:147], v[138:139], 0, v[140:141]
	v_lshlrev_b64 v[156:157], 13, v[136:137]
	v_or_b32_e32 v136, 3, v166
	global_load_dword v2, v[146:147], off
	v_lshl_add_u64 v[150:151], v[138:139], 0, v[154:155]
	v_ashrrev_i32_e32 v137, 31, v136
	global_load_dword v142, v[150:151], off
	v_lshl_add_u64 v[152:153], v[138:139], 0, v[156:157]
	v_lshlrev_b64 v[158:159], 13, v[136:137]
	global_load_dword v143, v[152:153], off
	v_lshl_add_u64 v[148:149], v[138:139], 0, v[158:159]
	global_load_dword v145, v[148:149], off
	global_load_dword v162, v[146:147], off offset:64
	global_load_dword v163, v[150:151], off offset:64
	global_load_dword v164, v[152:153], off offset:64
	global_load_dword v165, v[148:149], off offset:64
	v_lshl_add_u64 v[136:137], s[6:7], 0, v[0:1]
	v_lshl_add_u64 v[0:1], v[136:137], 0, v[140:141]
	v_or_b32_e32 v160, 16, v144
	v_ashrrev_i32_e32 v161, 31, v160
	v_readlane_b32 s48, v252, 2
	s_waitcnt vmcnt(0)
	v_add_f32_e32 v2, v132, v2
	global_store_dword v[0:1], v2, off sc1
	v_lshl_add_u64 v[0:1], v[136:137], 0, v[154:155]
	v_add_f32_e32 v2, v133, v142
	global_store_dword v[0:1], v2, off sc1
	v_lshl_add_u64 v[0:1], v[136:137], 0, v[156:157]
	v_add_f32_e32 v2, v134, v143
	global_store_dword v[0:1], v2, off sc1
	v_add_f32_e32 v2, v135, v145
	v_lshl_add_u64 v[0:1], v[136:137], 0, v[158:159]
	global_store_dword v[0:1], v2, off sc1
	v_lshl_add_u64 v[142:143], s[6:7], 0, v[140:141]
	v_lshlrev_b64 v[0:1], 2, v[160:161]
	v_add_f32_e32 v2, v128, v162
	v_lshl_add_u64 v[132:133], v[142:143], 0, v[0:1]
	v_lshl_add_u64 v[134:135], s[6:7], 0, v[154:155]
	global_store_dword v[132:133], v2, off sc1
	v_add_f32_e32 v2, v129, v163
	v_lshl_add_u64 v[128:129], v[134:135], 0, v[0:1]
	v_lshl_add_u64 v[132:133], s[6:7], 0, v[156:157]
	global_store_dword v[128:129], v2, off sc1
	v_add_f32_e32 v2, v130, v164
	v_lshl_add_u64 v[128:129], v[132:133], 0, v[0:1]
	global_store_dword v[128:129], v2, off sc1
	v_lshl_add_u64 v[128:129], s[6:7], 0, v[158:159]
	v_add_f32_e32 v2, v131, v165
	v_lshl_add_u64 v[130:131], v[128:129], 0, v[0:1]
	global_store_dword v[130:131], v2, off sc1
	v_or_b32_e32 v130, 16, v166
	v_ashrrev_i32_e32 v131, 31, v130
	v_or_b32_e32 v154, 17, v166
	v_lshlrev_b64 v[160:161], 13, v[130:131]
	v_ashrrev_i32_e32 v155, 31, v154
	v_or_b32_e32 v156, 18, v166
	v_lshl_add_u64 v[130:131], v[138:139], 0, v[160:161]
	v_lshlrev_b64 v[162:163], 13, v[154:155]
	v_ashrrev_i32_e32 v157, 31, v156
	global_load_dword v2, v[130:131], off
	v_lshl_add_u64 v[154:155], v[138:139], 0, v[162:163]
	v_lshlrev_b64 v[164:165], 13, v[156:157]
	global_load_dword v145, v[154:155], off
	v_lshl_add_u64 v[156:157], v[138:139], 0, v[164:165]
	global_load_dword v167, v[156:157], off
	v_or_b32_e32 v158, 19, v166
	v_ashrrev_i32_e32 v159, 31, v158
	v_lshlrev_b64 v[168:169], 13, v[158:159]
	v_lshl_add_u64 v[158:159], v[138:139], 0, v[168:169]
	global_load_dword v172, v[158:159], off
	global_load_dword v173, v[130:131], off offset:64
	global_load_dword v174, v[154:155], off offset:64
	global_load_dword v175, v[156:157], off offset:64
	global_load_dword v176, v[158:159], off offset:64
	v_lshl_add_u64 v[170:171], v[136:137], 0, v[160:161]
	v_lshl_add_u64 v[160:161], s[6:7], 0, v[160:161]
	s_waitcnt vmcnt(7)
	v_add_f32_e32 v2, v124, v2
	global_store_dword v[170:171], v2, off sc1
	s_waitcnt vmcnt(7)
	v_add_f32_e32 v2, v125, v145
	v_lshl_add_u64 v[124:125], v[136:137], 0, v[162:163]
	global_store_dword v[124:125], v2, off sc1
	s_waitcnt vmcnt(7)
	v_add_f32_e32 v2, v126, v167
	v_lshl_add_u64 v[124:125], v[136:137], 0, v[164:165]
	global_store_dword v[124:125], v2, off sc1
	s_waitcnt vmcnt(7)
	v_add_f32_e32 v2, v127, v172
	v_lshl_add_u64 v[124:125], v[136:137], 0, v[168:169]
	global_store_dword v[124:125], v2, off sc1
	s_waitcnt vmcnt(7)
	v_add_f32_e32 v2, v120, v173
	v_lshl_add_u64 v[124:125], v[160:161], 0, v[0:1]
	v_lshl_add_u64 v[126:127], s[6:7], 0, v[162:163]
	global_store_dword v[124:125], v2, off sc1
	s_waitcnt vmcnt(7)
	v_add_f32_e32 v2, v121, v174
	v_lshl_add_u64 v[120:121], v[126:127], 0, v[0:1]
	v_lshl_add_u64 v[124:125], s[6:7], 0, v[164:165]
	global_store_dword v[120:121], v2, off sc1
	s_waitcnt vmcnt(7)
	v_add_f32_e32 v2, v122, v175
	v_lshl_add_u64 v[120:121], v[124:125], 0, v[0:1]
	global_store_dword v[120:121], v2, off sc1
	v_lshl_add_u64 v[120:121], s[6:7], 0, v[168:169]
	s_waitcnt vmcnt(7)
; __device__ __forceinline__ float bf2f(u16 h) { return __uint_as_float(((unsigned)h) << 16); }
; __device__ __forceinline__ float sigmoidf_(float x) { return 1.f / (1.f + __expf(-x)); }
; template <int EPI>
; __device__ __forceinline__ void gemm_tile(const u16* __restrict__ A, long lda, const u16* __restrict__ Bt, long ldb, int K,
;                                           int brow, int bcol, const Epi& e, u16* shm) {
;     ...
;   for (int mh = 0; mh < 4; ++mh) {
;     float ta[4][2][4], tg[4][2][4];
; #pragma unroll
;     for (int m = mh; m < mh + 1; ++m)
; #pragma unroll
;     for (int n = 0; n < 2; ++n)
; #pragma unroll
;     for (int j = 0; j < 4; ++j) {
;       const int row = brow + ai * HALF + wr * 64 + m * 16 + fq * 4 + j, col = bcol + bj * HALF + wc * 32 + n * 16 + fr;
;       ta[m][n][j] = 0.f; tg[m][n][j] = 0.f;
;       if constexpr (EPI == EPI_RES) ta[m][n][j] = e.res[(long)row * D + col];
;       if constexpr (EPI == EPI_MRG1 || EPI == EPI_MRG2) ta[m][n][j] = e.cf[(long)row * D + col];
;       if constexpr (EPI == EPI_MRG0) tg[m][n][j] = bf2f(e.proj[(long)row * NC + OG + col]);
;       if constexpr (EPI == EPI_MRG1) tg[m][n][j] = bf2f(e.proj[(long)row * NC + OG + 2048 + col]);
;       if constexpr (EPI == EPI_MRG2) tg[m][n][j] = bf2f(e.proj[(long)row * NC + OG + 4096 + col]);
;     }
; #pragma unroll
;     for (int m = mh; m < mh + 1; ++m)
; #pragma unroll
;     for (int n = 0; n < 2; ++n)
; #pragma unroll
;     for (int j = 0; j < 4; ++j) {
;       const int row = brow + ai * HALF + wr * 64 + m * 16 + fq * 4 + j, col = bcol + bj * HALF + wc * 32 + n * 16 + fr;
;       const float v = acc[ai][bj][m][n][j];
;       if constexpr (EPI == EPI_RES) e.cf[(long)row * D + col] = ta[m][n][j] + v;
;       if constexpr (EPI == EPI_MRG0) e.cf[(long)row * D + col] = sigmoidf_(tg[m][n][j]) * v;
;       if constexpr (EPI == EPI_MRG1) e.cf[(long)row * D + col] = ta[m][n][j] + sigmoidf_(tg[m][n][j]) * v;
;       if constexpr (EPI == EPI_MRG2) e.cb[(long)row * D + col] = f2bf(ta[m][n][j] + sigmoidf_(tg[m][n][j]) * v);
;     }
	v_add_f32_e32 v2, v123, v176
	v_lshl_add_u64 v[122:123], v[120:121], 0, v[0:1]
	global_store_dword v[122:123], v2, off sc1
	v_or_b32_e32 v122, 32, v166
	v_ashrrev_i32_e32 v123, 31, v122
	v_or_b32_e32 v162, 33, v166
	v_lshlrev_b64 v[170:171], 13, v[122:123]
	v_ashrrev_i32_e32 v163, 31, v162
	v_or_b32_e32 v164, 34, v166
	v_lshl_add_u64 v[122:123], v[138:139], 0, v[170:171]
	v_lshlrev_b64 v[172:173], 13, v[162:163]
	v_ashrrev_i32_e32 v165, 31, v164
	global_load_dword v2, v[122:123], off
	v_lshl_add_u64 v[162:163], v[138:139], 0, v[172:173]
	v_lshlrev_b64 v[174:175], 13, v[164:165]
	global_load_dword v145, v[162:163], off
	v_lshl_add_u64 v[164:165], v[138:139], 0, v[174:175]
	global_load_dword v167, v[164:165], off
	v_or_b32_e32 v168, 35, v166
	v_ashrrev_i32_e32 v169, 31, v168
	v_lshlrev_b64 v[176:177], 13, v[168:169]
	v_lshl_add_u64 v[168:169], v[138:139], 0, v[176:177]
	global_load_dword v180, v[168:169], off
	global_load_dword v181, v[122:123], off offset:64
	global_load_dword v182, v[162:163], off offset:64
	global_load_dword v183, v[164:165], off offset:64
	global_load_dword v184, v[168:169], off offset:64
	v_lshl_add_u64 v[178:179], v[136:137], 0, v[170:171]
	v_lshl_add_u64 v[170:171], s[6:7], 0, v[170:171]
	s_waitcnt vmcnt(7)
	v_add_f32_e32 v2, v116, v2
	global_store_dword v[178:179], v2, off sc1
	s_waitcnt vmcnt(7)
	v_add_f32_e32 v2, v117, v145
	v_lshl_add_u64 v[116:117], v[136:137], 0, v[172:173]
	global_store_dword v[116:117], v2, off sc1
	s_waitcnt vmcnt(7)
	v_add_f32_e32 v2, v118, v167
	v_lshl_add_u64 v[116:117], v[136:137], 0, v[174:175]
	global_store_dword v[116:117], v2, off sc1
	s_waitcnt vmcnt(7)
	v_add_f32_e32 v2, v119, v180
	v_lshl_add_u64 v[116:117], v[136:137], 0, v[176:177]
	global_store_dword v[116:117], v2, off sc1
	s_waitcnt vmcnt(7)
	v_add_f32_e32 v2, v112, v181
	v_lshl_add_u64 v[116:117], v[170:171], 0, v[0:1]
	v_lshl_add_u64 v[118:119], s[6:7], 0, v[172:173]
	global_store_dword v[116:117], v2, off sc1
	s_waitcnt vmcnt(7)
	v_add_f32_e32 v2, v113, v182
	v_lshl_add_u64 v[112:113], v[118:119], 0, v[0:1]
	v_lshl_add_u64 v[116:117], s[6:7], 0, v[174:175]
	global_store_dword v[112:113], v2, off sc1
	s_waitcnt vmcnt(7)
	v_add_f32_e32 v2, v114, v183
	v_lshl_add_u64 v[112:113], v[116:117], 0, v[0:1]
	global_store_dword v[112:113], v2, off sc1
	v_lshl_add_u64 v[112:113], s[6:7], 0, v[176:177]
	s_waitcnt vmcnt(7)
	v_add_f32_e32 v2, v115, v184
	v_lshl_add_u64 v[114:115], v[112:113], 0, v[0:1]
	global_store_dword v[114:115], v2, off sc1
	v_or_b32_e32 v114, 48, v166
	v_ashrrev_i32_e32 v115, 31, v114
	v_or_b32_e32 v172, 49, v166
	v_lshlrev_b64 v[176:177], 13, v[114:115]
	v_ashrrev_i32_e32 v173, 31, v172
	v_or_b32_e32 v174, 50, v166
	v_lshl_add_u64 v[114:115], v[138:139], 0, v[176:177]
	v_lshlrev_b64 v[178:179], 13, v[172:173]
	v_ashrrev_i32_e32 v175, 31, v174
	global_load_dword v2, v[114:115], off
	v_lshl_add_u64 v[172:173], v[138:139], 0, v[178:179]
	v_lshlrev_b64 v[180:181], 13, v[174:175]
	global_load_dword v145, v[172:173], off
	v_lshl_add_u64 v[174:175], v[138:139], 0, v[180:181]
	global_load_dword v186, v[174:175], off
	v_or_b32_e32 v166, 51, v166
	v_ashrrev_i32_e32 v167, 31, v166
	v_lshlrev_b64 v[182:183], 13, v[166:167]
	v_lshl_add_u64 v[166:167], v[138:139], 0, v[182:183]
	global_load_dword v187, v[166:167], off
	global_load_dword v192, v[114:115], off offset:64
	global_load_dword v193, v[172:173], off offset:64
	global_load_dword v194, v[174:175], off offset:64
	global_load_dword v195, v[166:167], off offset:64
	v_lshl_add_u64 v[184:185], v[136:137], 0, v[176:177]
	s_waitcnt vmcnt(7)
	v_add_f32_e32 v2, v108, v2
	global_store_dword v[184:185], v2, off sc1
	s_waitcnt vmcnt(7)
	v_add_f32_e32 v2, v109, v145
	v_lshl_add_u64 v[108:109], v[136:137], 0, v[178:179]
	global_store_dword v[108:109], v2, off sc1
	s_waitcnt vmcnt(7)
	v_add_f32_e32 v2, v110, v186
	v_lshl_add_u64 v[108:109], v[136:137], 0, v[180:181]
	global_store_dword v[108:109], v2, off sc1
	s_waitcnt vmcnt(7)
	v_add_f32_e32 v2, v111, v187
	v_lshl_add_u64 v[108:109], v[136:137], 0, v[182:183]
	global_store_dword v[108:109], v2, off sc1
	v_lshl_add_u64 v[108:109], s[6:7], 0, v[176:177]
	s_waitcnt vmcnt(7)
	v_add_f32_e32 v2, v104, v192
	v_lshl_add_u64 v[110:111], v[108:109], 0, v[0:1]
	global_store_dword v[110:111], v2, off sc1
	v_lshl_add_u64 v[110:111], s[6:7], 0, v[178:179]
	s_waitcnt vmcnt(7)
	v_add_f32_e32 v2, v105, v193
	v_lshl_add_u64 v[104:105], v[110:111], 0, v[0:1]
	v_lshl_add_u64 v[176:177], s[6:7], 0, v[180:181]
	global_store_dword v[104:105], v2, off sc1
	s_waitcnt vmcnt(7)
	v_add_f32_e32 v2, v106, v194
	v_lshl_add_u64 v[104:105], v[176:177], 0, v[0:1]
	global_store_dword v[104:105], v2, off sc1
	s_waitcnt vmcnt(7)
	v_add_f32_e32 v2, v107, v195
	v_lshl_add_u64 v[106:107], s[6:7], 0, v[182:183]
	v_lshl_add_u64 v[104:105], v[106:107], 0, v[0:1]
	global_store_dword v[104:105], v2, off sc1
	global_load_dword v2, v[146:147], off offset:512
	s_nop 0
	global_load_dword v178, v[150:151], off offset:512
	global_load_dword v179, v[152:153], off offset:512
	global_load_dword v180, v[148:149], off offset:512
	global_load_dword v181, v[146:147], off offset:576
	s_nop 0
	global_load_dword v150, v[150:151], off offset:576
	s_nop 0
	global_load_dword v151, v[152:153], off offset:576
	s_nop 0
	global_load_dword v148, v[148:149], off offset:576
	v_or_b32_e32 v104, 0x80, v144
	v_ashrrev_i32_e32 v105, 31, v104
	v_lshlrev_b64 v[104:105], 2, v[104:105]
	v_lshl_add_u64 v[146:147], v[142:143], 0, v[104:105]
	v_or_b32_e32 v144, 0x90, v144
	v_ashrrev_i32_e32 v145, 31, v144
	s_waitcnt vmcnt(7)
	v_add_f32_e32 v2, v100, v2
	global_store_dword v[146:147], v2, off sc1
	s_waitcnt vmcnt(7)
; __device__ __forceinline__ float bf2f(u16 h) { return __uint_as_float(((unsigned)h) << 16); }
; __device__ __forceinline__ float sigmoidf_(float x) { return 1.f / (1.f + __expf(-x)); }
; template <int EPI>
; __device__ __forceinline__ void gemm_tile(const u16* __restrict__ A, long lda, const u16* __restrict__ Bt, long ldb, int K,
;                                           int brow, int bcol, const Epi& e, u16* shm) {
;     ...
;   for (int mh = 0; mh < 4; ++mh) {
;     float ta[4][2][4], tg[4][2][4];
; #pragma unroll
;     for (int m = mh; m < mh + 1; ++m)
; #pragma unroll
;     for (int n = 0; n < 2; ++n)
; #pragma unroll
;     for (int j = 0; j < 4; ++j) {
;       const int row = brow + ai * HALF + wr * 64 + m * 16 + fq * 4 + j, col = bcol + bj * HALF + wc * 32 + n * 16 + fr;
;       ta[m][n][j] = 0.f; tg[m][n][j] = 0.f;
;       if constexpr (EPI == EPI_RES) ta[m][n][j] = e.res[(long)row * D + col];
;       if constexpr (EPI == EPI_MRG1 || EPI == EPI_MRG2) ta[m][n][j] = e.cf[(long)row * D + col];
;       if constexpr (EPI == EPI_MRG0) tg[m][n][j] = bf2f(e.proj[(long)row * NC + OG + col]);
;       if constexpr (EPI == EPI_MRG1) tg[m][n][j] = bf2f(e.proj[(long)row * NC + OG + 2048 + col]);
;       if constexpr (EPI == EPI_MRG2) tg[m][n][j] = bf2f(e.proj[(long)row * NC + OG + 4096 + col]);
;     }
; #pragma unroll
;     for (int m = mh; m < mh + 1; ++m)
; #pragma unroll
;     for (int n = 0; n < 2; ++n)
; #pragma unroll
;     for (int j = 0; j < 4; ++j) {
;       const int row = brow + ai * HALF + wr * 64 + m * 16 + fq * 4 + j, col = bcol + bj * HALF + wc * 32 + n * 16 + fr;
;       const float v = acc[ai][bj][m][n][j];
;       if constexpr (EPI == EPI_RES) e.cf[(long)row * D + col] = ta[m][n][j] + v;
;       if constexpr (EPI == EPI_MRG0) e.cf[(long)row * D + col] = sigmoidf_(tg[m][n][j]) * v;
;       if constexpr (EPI == EPI_MRG1) e.cf[(long)row * D + col] = ta[m][n][j] + sigmoidf_(tg[m][n][j]) * v;
;       if constexpr (EPI == EPI_MRG2) e.cb[(long)row * D + col] = f2bf(ta[m][n][j] + sigmoidf_(tg[m][n][j]) * v);
;     }
	v_add_f32_e32 v2, v101, v178
	v_lshl_add_u64 v[100:101], v[134:135], 0, v[104:105]
	global_store_dword v[100:101], v2, off sc1
	s_waitcnt vmcnt(7)
	v_add_f32_e32 v2, v102, v179
	v_lshl_add_u64 v[100:101], v[132:133], 0, v[104:105]
	global_store_dword v[100:101], v2, off sc1
	s_waitcnt vmcnt(7)
	v_add_f32_e32 v2, v103, v180
	v_lshl_add_u64 v[100:101], v[128:129], 0, v[104:105]
	global_store_dword v[100:101], v2, off sc1
	v_lshlrev_b64 v[100:101], 2, v[144:145]
	s_waitcnt vmcnt(7)
	v_add_f32_e32 v2, v96, v181
	v_lshl_add_u64 v[102:103], v[142:143], 0, v[100:101]
	global_store_dword v[102:103], v2, off sc1
	s_waitcnt vmcnt(7)
	v_add_f32_e32 v2, v97, v150
	v_lshl_add_u64 v[96:97], v[134:135], 0, v[100:101]
	global_store_dword v[96:97], v2, off sc1
	s_waitcnt vmcnt(7)
	v_add_f32_e32 v2, v98, v151
	v_lshl_add_u64 v[96:97], v[132:133], 0, v[100:101]
	global_store_dword v[96:97], v2, off sc1
	s_waitcnt vmcnt(7)
	v_add_f32_e32 v2, v99, v148
	v_lshl_add_u64 v[96:97], v[128:129], 0, v[100:101]
	global_store_dword v[96:97], v2, off sc1
	global_load_dword v2, v[130:131], off offset:512
	s_nop 0
	global_load_dword v98, v[154:155], off offset:512
	global_load_dword v99, v[156:157], off offset:512
	global_load_dword v102, v[158:159], off offset:512
	global_load_dword v103, v[130:131], off offset:576
	global_load_dword v128, v[154:155], off offset:576
	global_load_dword v129, v[156:157], off offset:576
	s_nop 0
	global_load_dword v130, v[158:159], off offset:576
	v_lshl_add_u64 v[96:97], v[160:161], 0, v[104:105]
	s_waitcnt vmcnt(7)
	v_add_f32_e32 v2, v92, v2
	global_store_dword v[96:97], v2, off sc1
	s_waitcnt vmcnt(7)
	v_add_f32_e32 v2, v93, v98
	v_lshl_add_u64 v[92:93], v[126:127], 0, v[104:105]
	global_store_dword v[92:93], v2, off sc1
	s_waitcnt vmcnt(7)
	v_add_f32_e32 v2, v94, v99
	v_lshl_add_u64 v[92:93], v[124:125], 0, v[104:105]
	global_store_dword v[92:93], v2, off sc1
	s_waitcnt vmcnt(7)
	v_add_f32_e32 v2, v95, v102
	v_lshl_add_u64 v[92:93], v[120:121], 0, v[104:105]
	global_store_dword v[92:93], v2, off sc1
	s_waitcnt vmcnt(7)
	v_add_f32_e32 v2, v88, v103
	v_lshl_add_u64 v[92:93], v[160:161], 0, v[100:101]
	global_store_dword v[92:93], v2, off sc1
	s_waitcnt vmcnt(7)
	v_add_f32_e32 v2, v89, v128
	v_lshl_add_u64 v[88:89], v[126:127], 0, v[100:101]
	global_store_dword v[88:89], v2, off sc1
	s_waitcnt vmcnt(7)
	v_add_f32_e32 v2, v90, v129
	v_lshl_add_u64 v[88:89], v[124:125], 0, v[100:101]
	global_store_dword v[88:89], v2, off sc1
	s_waitcnt vmcnt(7)
	v_add_f32_e32 v2, v91, v130
	v_lshl_add_u64 v[88:89], v[120:121], 0, v[100:101]
	global_store_dword v[88:89], v2, off sc1
	global_load_dword v2, v[122:123], off offset:512
	s_nop 0
	global_load_dword v90, v[162:163], off offset:512
	global_load_dword v91, v[164:165], off offset:512
	global_load_dword v92, v[168:169], off offset:512
	global_load_dword v93, v[122:123], off offset:576
	global_load_dword v94, v[162:163], off offset:576
	global_load_dword v95, v[164:165], off offset:576
	global_load_dword v96, v[168:169], off offset:576
	v_lshl_add_u64 v[88:89], v[170:171], 0, v[104:105]
	s_waitcnt vmcnt(7)
	v_add_f32_e32 v2, v84, v2
	global_store_dword v[88:89], v2, off sc1
	s_waitcnt vmcnt(7)
	v_add_f32_e32 v2, v85, v90
	v_lshl_add_u64 v[84:85], v[118:119], 0, v[104:105]
	global_store_dword v[84:85], v2, off sc1
	s_waitcnt vmcnt(7)
	v_add_f32_e32 v2, v86, v91
	v_lshl_add_u64 v[84:85], v[116:117], 0, v[104:105]
	global_store_dword v[84:85], v2, off sc1
	s_waitcnt vmcnt(7)
	v_add_f32_e32 v2, v87, v92
	v_lshl_add_u64 v[84:85], v[112:113], 0, v[104:105]
	global_store_dword v[84:85], v2, off sc1
	s_waitcnt vmcnt(7)
	v_add_f32_e32 v2, v80, v93
	v_lshl_add_u64 v[84:85], v[170:171], 0, v[100:101]
	global_store_dword v[84:85], v2, off sc1
	s_waitcnt vmcnt(7)
	v_add_f32_e32 v2, v81, v94
	v_lshl_add_u64 v[80:81], v[118:119], 0, v[100:101]
	global_store_dword v[80:81], v2, off sc1
	s_waitcnt vmcnt(7)
	v_add_f32_e32 v2, v82, v95
	v_lshl_add_u64 v[80:81], v[116:117], 0, v[100:101]
	global_store_dword v[80:81], v2, off sc1
	s_waitcnt vmcnt(7)
	v_add_f32_e32 v2, v83, v96
	v_lshl_add_u64 v[80:81], v[112:113], 0, v[100:101]
	global_store_dword v[80:81], v2, off sc1
	global_load_dword v2, v[114:115], off offset:512
	s_nop 0
	global_load_dword v82, v[172:173], off offset:512
	global_load_dword v83, v[174:175], off offset:512
	global_load_dword v84, v[166:167], off offset:512
	global_load_dword v85, v[114:115], off offset:576
	global_load_dword v86, v[172:173], off offset:576
	global_load_dword v87, v[174:175], off offset:576
	global_load_dword v88, v[166:167], off offset:576
	v_lshl_add_u64 v[80:81], v[108:109], 0, v[104:105]
	s_waitcnt vmcnt(7)
	v_add_f32_e32 v2, v76, v2
	global_store_dword v[80:81], v2, off sc1
	s_waitcnt vmcnt(7)
	v_add_f32_e32 v2, v77, v82
	v_lshl_add_u64 v[76:77], v[110:111], 0, v[104:105]
	global_store_dword v[76:77], v2, off sc1
	s_waitcnt vmcnt(7)
	v_add_f32_e32 v2, v78, v83
	v_lshl_add_u64 v[76:77], v[176:177], 0, v[104:105]
	global_store_dword v[76:77], v2, off sc1
	s_waitcnt vmcnt(7)
	v_add_f32_e32 v2, v79, v84
	v_lshl_add_u64 v[76:77], v[106:107], 0, v[104:105]
	global_store_dword v[76:77], v2, off sc1
	s_waitcnt vmcnt(7)
	v_add_f32_e32 v2, v72, v85
	v_lshl_add_u64 v[76:77], v[108:109], 0, v[100:101]
	global_store_dword v[76:77], v2, off sc1
	s_waitcnt vmcnt(7)
	v_add_f32_e32 v2, v73, v86
	v_lshl_add_u64 v[72:73], v[110:111], 0, v[100:101]
	global_store_dword v[72:73], v2, off sc1
	s_waitcnt vmcnt(7)
	v_add_f32_e32 v2, v74, v87
	v_lshl_add_u64 v[72:73], v[176:177], 0, v[100:101]
	global_store_dword v[72:73], v2, off sc1
	s_waitcnt vmcnt(7)
; __device__ __forceinline__ float bf2f(u16 h) { return __uint_as_float(((unsigned)h) << 16); }
; __device__ __forceinline__ float sigmoidf_(float x) { return 1.f / (1.f + __expf(-x)); }
; template <int EPI>
; __device__ __forceinline__ void gemm_tile(const u16* __restrict__ A, long lda, const u16* __restrict__ Bt, long ldb, int K,
;                                           int brow, int bcol, const Epi& e, u16* shm) {
;     ...
;   for (int mh = 0; mh < 4; ++mh) {
;     float ta[4][2][4], tg[4][2][4];
; #pragma unroll
;     for (int m = mh; m < mh + 1; ++m)
; #pragma unroll
;     for (int n = 0; n < 2; ++n)
; #pragma unroll
;     for (int j = 0; j < 4; ++j) {
;       const int row = brow + ai * HALF + wr * 64 + m * 16 + fq * 4 + j, col = bcol + bj * HALF + wc * 32 + n * 16 + fr;
;       ta[m][n][j] = 0.f; tg[m][n][j] = 0.f;
;       if constexpr (EPI == EPI_RES) ta[m][n][j] = e.res[(long)row * D + col];
;       if constexpr (EPI == EPI_MRG1 || EPI == EPI_MRG2) ta[m][n][j] = e.cf[(long)row * D + col];
;       if constexpr (EPI == EPI_MRG0) tg[m][n][j] = bf2f(e.proj[(long)row * NC + OG + col]);
;       if constexpr (EPI == EPI_MRG1) tg[m][n][j] = bf2f(e.proj[(long)row * NC + OG + 2048 + col]);
;       if constexpr (EPI == EPI_MRG2) tg[m][n][j] = bf2f(e.proj[(long)row * NC + OG + 4096 + col]);
;     }
; #pragma unroll
;     for (int m = mh; m < mh + 1; ++m)
; #pragma unroll
;     for (int n = 0; n < 2; ++n)
; #pragma unroll
;     for (int j = 0; j < 4; ++j) {
;       const int row = brow + ai * HALF + wr * 64 + m * 16 + fq * 4 + j, col = bcol + bj * HALF + wc * 32 + n * 16 + fr;
;       const float v = acc[ai][bj][m][n][j];
;       if constexpr (EPI == EPI_RES) e.cf[(long)row * D + col] = ta[m][n][j] + v;
;       if constexpr (EPI == EPI_MRG0) e.cf[(long)row * D + col] = sigmoidf_(tg[m][n][j]) * v;
;       if constexpr (EPI == EPI_MRG1) e.cf[(long)row * D + col] = ta[m][n][j] + sigmoidf_(tg[m][n][j]) * v;
;       if constexpr (EPI == EPI_MRG2) e.cb[(long)row * D + col] = f2bf(ta[m][n][j] + sigmoidf_(tg[m][n][j]) * v);
;     }
	v_add_f32_e32 v2, v75, v88
	v_lshl_add_u64 v[72:73], v[106:107], 0, v[100:101]
	v_lshl_add_u64 v[80:81], v[140:141], 0, s[0:1]
	s_mov_b64 s[0:1], 0x102000
	global_store_dword v[72:73], v2, off sc1
	v_lshl_add_u64 v[72:73], v[138:139], 0, v[80:81]
	v_lshl_add_u64 v[82:83], v[140:141], 0, s[0:1]
	s_mov_b64 s[0:1], 0x104000
	global_load_dword v2, v[72:73], off
	v_lshl_add_u64 v[74:75], v[138:139], 0, v[82:83]
	v_lshl_add_u64 v[84:85], v[140:141], 0, s[0:1]
	global_load_dword v90, v[74:75], off
	v_lshl_add_u64 v[76:77], v[138:139], 0, v[84:85]
	global_load_dword v91, v[76:77], off
	s_mov_b64 s[0:1], 0x106000
	v_lshl_add_u64 v[86:87], v[140:141], 0, s[0:1]
	v_lshl_add_u64 v[78:79], v[138:139], 0, v[86:87]
	global_load_dword v92, v[78:79], off
	global_load_dword v93, v[72:73], off offset:64
	global_load_dword v94, v[74:75], off offset:64
	global_load_dword v95, v[76:77], off offset:64
	global_load_dword v96, v[78:79], off offset:64
	v_lshl_add_u64 v[88:89], v[136:137], 0, v[80:81]
	v_lshl_add_u64 v[80:81], s[6:7], 0, v[80:81]
	s_mov_b64 s[0:1], 0x120000
	s_waitcnt vmcnt(7)
	v_add_f32_e32 v2, v68, v2
	global_store_dword v[88:89], v2, off sc1
	v_lshl_add_u64 v[88:89], v[140:141], 0, s[0:1]
	s_waitcnt vmcnt(7)
	v_add_f32_e32 v2, v69, v90
	v_lshl_add_u64 v[68:69], v[136:137], 0, v[82:83]
	global_store_dword v[68:69], v2, off sc1
	s_waitcnt vmcnt(7)
	v_add_f32_e32 v2, v70, v91
	v_lshl_add_u64 v[68:69], v[136:137], 0, v[84:85]
	global_store_dword v[68:69], v2, off sc1
	s_waitcnt vmcnt(7)
	v_add_f32_e32 v2, v71, v92
	v_lshl_add_u64 v[68:69], v[136:137], 0, v[86:87]
	global_store_dword v[68:69], v2, off sc1
	s_waitcnt vmcnt(7)
	v_add_f32_e32 v2, v64, v93
	v_lshl_add_u64 v[68:69], v[80:81], 0, v[0:1]
	v_lshl_add_u64 v[70:71], s[6:7], 0, v[82:83]
	global_store_dword v[68:69], v2, off sc1
	s_waitcnt vmcnt(7)
	v_add_f32_e32 v2, v65, v94
	v_lshl_add_u64 v[64:65], v[70:71], 0, v[0:1]
	v_lshl_add_u64 v[68:69], s[6:7], 0, v[84:85]
	global_store_dword v[64:65], v2, off sc1
	s_waitcnt vmcnt(7)
	v_add_f32_e32 v2, v66, v95
	v_lshl_add_u64 v[64:65], v[68:69], 0, v[0:1]
	global_store_dword v[64:65], v2, off sc1
	v_lshl_add_u64 v[64:65], s[6:7], 0, v[86:87]
	s_waitcnt vmcnt(7)
	v_add_f32_e32 v2, v67, v96
	v_lshl_add_u64 v[66:67], v[64:65], 0, v[0:1]
	s_mov_b64 s[0:1], 0x122000
	global_store_dword v[66:67], v2, off sc1
	v_lshl_add_u64 v[66:67], v[138:139], 0, v[88:89]
	v_lshl_add_u64 v[90:91], v[140:141], 0, s[0:1]
	s_mov_b64 s[0:1], 0x124000
	global_load_dword v2, v[66:67], off
	v_lshl_add_u64 v[82:83], v[138:139], 0, v[90:91]
	v_lshl_add_u64 v[92:93], v[140:141], 0, s[0:1]
	global_load_dword v98, v[82:83], off
	v_lshl_add_u64 v[84:85], v[138:139], 0, v[92:93]
	global_load_dword v99, v[84:85], off
	s_mov_b64 s[0:1], 0x126000
	v_lshl_add_u64 v[94:95], v[140:141], 0, s[0:1]
	v_lshl_add_u64 v[86:87], v[138:139], 0, v[94:95]
	global_load_dword v102, v[86:87], off
	global_load_dword v103, v[66:67], off offset:64
	global_load_dword v106, v[82:83], off offset:64
	global_load_dword v107, v[84:85], off offset:64
	global_load_dword v108, v[86:87], off offset:64
	v_lshl_add_u64 v[96:97], v[136:137], 0, v[88:89]
	v_lshl_add_u64 v[88:89], s[6:7], 0, v[88:89]
	s_mov_b64 s[0:1], 0x140000
	s_waitcnt vmcnt(7)
	v_add_f32_e32 v2, v60, v2
	global_store_dword v[96:97], v2, off sc1
	v_lshl_add_u64 v[96:97], v[140:141], 0, s[0:1]
	s_waitcnt vmcnt(7)
	v_add_f32_e32 v2, v61, v98
	v_lshl_add_u64 v[60:61], v[136:137], 0, v[90:91]
	global_store_dword v[60:61], v2, off sc1
	s_waitcnt vmcnt(7)
	v_add_f32_e32 v2, v62, v99
	v_lshl_add_u64 v[60:61], v[136:137], 0, v[92:93]
	global_store_dword v[60:61], v2, off sc1
	s_waitcnt vmcnt(7)
	v_add_f32_e32 v2, v63, v102
	v_lshl_add_u64 v[60:61], v[136:137], 0, v[94:95]
	global_store_dword v[60:61], v2, off sc1
	s_waitcnt vmcnt(7)
	v_add_f32_e32 v2, v56, v103
	v_lshl_add_u64 v[60:61], v[88:89], 0, v[0:1]
	v_lshl_add_u64 v[62:63], s[6:7], 0, v[90:91]
	global_store_dword v[60:61], v2, off sc1
	s_waitcnt vmcnt(7)
	v_add_f32_e32 v2, v57, v106
	v_lshl_add_u64 v[56:57], v[62:63], 0, v[0:1]
	v_lshl_add_u64 v[60:61], s[6:7], 0, v[92:93]
	global_store_dword v[56:57], v2, off sc1
	s_waitcnt vmcnt(7)
	v_add_f32_e32 v2, v58, v107
	v_lshl_add_u64 v[56:57], v[60:61], 0, v[0:1]
	global_store_dword v[56:57], v2, off sc1
	v_lshl_add_u64 v[56:57], s[6:7], 0, v[94:95]
	s_waitcnt vmcnt(7)
	v_add_f32_e32 v2, v59, v108
	v_lshl_add_u64 v[58:59], v[56:57], 0, v[0:1]
	s_mov_b64 s[0:1], 0x142000
	global_store_dword v[58:59], v2, off sc1
	v_lshl_add_u64 v[58:59], v[138:139], 0, v[96:97]
	v_lshl_add_u64 v[98:99], v[140:141], 0, s[0:1]
	s_mov_b64 s[0:1], 0x144000
	global_load_dword v2, v[58:59], off
	v_lshl_add_u64 v[90:91], v[138:139], 0, v[98:99]
	v_lshl_add_u64 v[102:103], v[140:141], 0, s[0:1]
	global_load_dword v110, v[90:91], off
	v_lshl_add_u64 v[92:93], v[138:139], 0, v[102:103]
	global_load_dword v111, v[92:93], off
	s_mov_b64 s[0:1], 0x146000
	v_lshl_add_u64 v[106:107], v[140:141], 0, s[0:1]
	v_lshl_add_u64 v[94:95], v[138:139], 0, v[106:107]
	global_load_dword v112, v[94:95], off
	global_load_dword v113, v[58:59], off offset:64
	global_load_dword v114, v[90:91], off offset:64
	global_load_dword v115, v[92:93], off offset:64
	global_load_dword v116, v[94:95], off offset:64
	v_lshl_add_u64 v[108:109], v[136:137], 0, v[96:97]
	v_lshl_add_u64 v[96:97], s[6:7], 0, v[96:97]
	s_mov_b64 s[0:1], 0x160000
	s_waitcnt vmcnt(7)
	v_add_f32_e32 v2, v52, v2
	global_store_dword v[108:109], v2, off sc1
	s_waitcnt vmcnt(7)
	v_add_f32_e32 v2, v53, v110
	v_lshl_add_u64 v[52:53], v[136:137], 0, v[98:99]
	global_store_dword v[52:53], v2, off sc1
	s_waitcnt vmcnt(7)
; __device__ __forceinline__ float bf2f(u16 h) { return __uint_as_float(((unsigned)h) << 16); }
; __device__ __forceinline__ float sigmoidf_(float x) { return 1.f / (1.f + __expf(-x)); }
; template <int EPI>
; __device__ __forceinline__ void gemm_tile(const u16* __restrict__ A, long lda, const u16* __restrict__ Bt, long ldb, int K,
;                                           int brow, int bcol, const Epi& e, u16* shm) {
;     ...
;   for (int mh = 0; mh < 4; ++mh) {
;     float ta[4][2][4], tg[4][2][4];
; #pragma unroll
;     for (int m = mh; m < mh + 1; ++m)
; #pragma unroll
;     for (int n = 0; n < 2; ++n)
; #pragma unroll
;     for (int j = 0; j < 4; ++j) {
;       const int row = brow + ai * HALF + wr * 64 + m * 16 + fq * 4 + j, col = bcol + bj * HALF + wc * 32 + n * 16 + fr;
;       ta[m][n][j] = 0.f; tg[m][n][j] = 0.f;
;       if constexpr (EPI == EPI_RES) ta[m][n][j] = e.res[(long)row * D + col];
;       if constexpr (EPI == EPI_MRG1 || EPI == EPI_MRG2) ta[m][n][j] = e.cf[(long)row * D + col];
;       if constexpr (EPI == EPI_MRG0) tg[m][n][j] = bf2f(e.proj[(long)row * NC + OG + col]);
;       if constexpr (EPI == EPI_MRG1) tg[m][n][j] = bf2f(e.proj[(long)row * NC + OG + 2048 + col]);
;       if constexpr (EPI == EPI_MRG2) tg[m][n][j] = bf2f(e.proj[(long)row * NC + OG + 4096 + col]);
;     }
; #pragma unroll
;     for (int m = mh; m < mh + 1; ++m)
; #pragma unroll
;     for (int n = 0; n < 2; ++n)
; #pragma unroll
;     for (int j = 0; j < 4; ++j) {
;       const int row = brow + ai * HALF + wr * 64 + m * 16 + fq * 4 + j, col = bcol + bj * HALF + wc * 32 + n * 16 + fr;
;       const float v = acc[ai][bj][m][n][j];
;       if constexpr (EPI == EPI_RES) e.cf[(long)row * D + col] = ta[m][n][j] + v;
;       if constexpr (EPI == EPI_MRG0) e.cf[(long)row * D + col] = sigmoidf_(tg[m][n][j]) * v;
;       if constexpr (EPI == EPI_MRG1) e.cf[(long)row * D + col] = ta[m][n][j] + sigmoidf_(tg[m][n][j]) * v;
;       if constexpr (EPI == EPI_MRG2) e.cb[(long)row * D + col] = f2bf(ta[m][n][j] + sigmoidf_(tg[m][n][j]) * v);
;     }
	v_add_f32_e32 v2, v54, v111
	v_lshl_add_u64 v[52:53], v[136:137], 0, v[102:103]
	global_store_dword v[52:53], v2, off sc1
	s_waitcnt vmcnt(7)
	v_add_f32_e32 v2, v55, v112
	v_lshl_add_u64 v[52:53], v[136:137], 0, v[106:107]
	global_store_dword v[52:53], v2, off sc1
	s_waitcnt vmcnt(7)
	v_add_f32_e32 v2, v48, v113
	v_lshl_add_u64 v[52:53], v[96:97], 0, v[0:1]
	v_lshl_add_u64 v[54:55], s[6:7], 0, v[98:99]
	global_store_dword v[52:53], v2, off sc1
	s_waitcnt vmcnt(7)
	v_add_f32_e32 v2, v49, v114
	v_lshl_add_u64 v[48:49], v[54:55], 0, v[0:1]
	v_lshl_add_u64 v[52:53], s[6:7], 0, v[102:103]
	global_store_dword v[48:49], v2, off sc1
	s_waitcnt vmcnt(7)
	v_add_f32_e32 v2, v50, v115
	v_lshl_add_u64 v[48:49], v[52:53], 0, v[0:1]
	global_store_dword v[48:49], v2, off sc1
	v_lshl_add_u64 v[48:49], s[6:7], 0, v[106:107]
	s_waitcnt vmcnt(7)
	v_add_f32_e32 v2, v51, v116
	v_lshl_add_u64 v[50:51], v[48:49], 0, v[0:1]
	v_lshl_add_u64 v[110:111], v[140:141], 0, s[0:1]
	s_mov_b64 s[0:1], 0x162000
	global_store_dword v[50:51], v2, off sc1
	v_lshl_add_u64 v[50:51], v[138:139], 0, v[110:111]
	v_lshl_add_u64 v[112:113], v[140:141], 0, s[0:1]
	s_mov_b64 s[0:1], 0x164000
	global_load_dword v2, v[50:51], off
	v_lshl_add_u64 v[98:99], v[138:139], 0, v[112:113]
	v_lshl_add_u64 v[114:115], v[140:141], 0, s[0:1]
	global_load_dword v118, v[98:99], off
	v_lshl_add_u64 v[102:103], v[138:139], 0, v[114:115]
	global_load_dword v119, v[102:103], off
	s_mov_b64 s[0:1], 0x166000
	v_lshl_add_u64 v[108:109], v[140:141], 0, s[0:1]
	v_lshl_add_u64 v[106:107], v[138:139], 0, v[108:109]
	global_load_dword v120, v[106:107], off
	global_load_dword v121, v[50:51], off offset:64
	global_load_dword v122, v[98:99], off offset:64
	global_load_dword v123, v[102:103], off offset:64
	global_load_dword v124, v[106:107], off offset:64
	v_lshl_add_u64 v[116:117], v[136:137], 0, v[110:111]
	s_mov_b32 s0, s48
	s_waitcnt vmcnt(7)
	v_add_f32_e32 v2, v44, v2
	global_store_dword v[116:117], v2, off sc1
	s_waitcnt vmcnt(7)
	v_add_f32_e32 v2, v45, v118
	v_lshl_add_u64 v[44:45], v[136:137], 0, v[112:113]
	global_store_dword v[44:45], v2, off sc1
	s_waitcnt vmcnt(7)
	v_add_f32_e32 v2, v46, v119
	v_lshl_add_u64 v[44:45], v[136:137], 0, v[114:115]
	global_store_dword v[44:45], v2, off sc1
	s_waitcnt vmcnt(7)
	v_add_f32_e32 v2, v47, v120
	v_lshl_add_u64 v[44:45], v[136:137], 0, v[108:109]
	global_store_dword v[44:45], v2, off sc1
	v_lshl_add_u64 v[44:45], s[6:7], 0, v[110:111]
	s_waitcnt vmcnt(7)
	v_add_f32_e32 v2, v40, v121
	v_lshl_add_u64 v[46:47], v[44:45], 0, v[0:1]
	global_store_dword v[46:47], v2, off sc1
	s_waitcnt vmcnt(7)
	v_add_f32_e32 v2, v41, v122
	v_lshl_add_u64 v[40:41], s[6:7], 0, v[112:113]
	v_lshl_add_u64 v[46:47], v[40:41], 0, v[0:1]
	global_store_dword v[46:47], v2, off sc1
	v_lshl_add_u64 v[46:47], s[6:7], 0, v[114:115]
	s_waitcnt vmcnt(7)
	v_add_f32_e32 v2, v42, v123
	v_lshl_add_u64 v[110:111], v[46:47], 0, v[0:1]
	global_store_dword v[110:111], v2, off sc1
	s_waitcnt vmcnt(7)
	v_add_f32_e32 v2, v43, v124
	v_lshl_add_u64 v[42:43], s[6:7], 0, v[108:109]
	v_lshl_add_u64 v[0:1], v[42:43], 0, v[0:1]
	global_store_dword v[0:1], v2, off sc1
	global_load_dword v0, v[72:73], off offset:512
	s_nop 0
	global_load_dword v2, v[74:75], off offset:512
	global_load_dword v108, v[76:77], off offset:512
	global_load_dword v109, v[78:79], off offset:512
	s_nop 0
	global_load_dword v72, v[72:73], off offset:576
	s_nop 0
	global_load_dword v73, v[74:75], off offset:576
	s_nop 0
	global_load_dword v74, v[76:77], off offset:576
	global_load_dword v75, v[78:79], off offset:576
	s_waitcnt vmcnt(7)
	v_add_f32_e32 v36, v36, v0
	v_lshl_add_u64 v[0:1], v[80:81], 0, v[104:105]
	global_store_dword v[0:1], v36, off sc1
	s_waitcnt vmcnt(7)
	v_add_f32_e32 v2, v37, v2
	v_lshl_add_u64 v[0:1], v[70:71], 0, v[104:105]
	global_store_dword v[0:1], v2, off sc1
	s_waitcnt vmcnt(7)
	v_add_f32_e32 v2, v38, v108
	v_lshl_add_u64 v[0:1], v[68:69], 0, v[104:105]
	global_store_dword v[0:1], v2, off sc1
	s_waitcnt vmcnt(7)
	v_add_f32_e32 v2, v39, v109
	v_lshl_add_u64 v[0:1], v[64:65], 0, v[104:105]
	global_store_dword v[0:1], v2, off sc1
	s_waitcnt vmcnt(7)
	v_add_f32_e32 v2, v32, v72
	v_lshl_add_u64 v[0:1], v[80:81], 0, v[100:101]
	global_store_dword v[0:1], v2, off sc1
	s_waitcnt vmcnt(7)
	v_add_f32_e32 v2, v33, v73
	v_lshl_add_u64 v[0:1], v[70:71], 0, v[100:101]
	global_store_dword v[0:1], v2, off sc1
	s_waitcnt vmcnt(7)
	v_add_f32_e32 v2, v34, v74
	v_lshl_add_u64 v[0:1], v[68:69], 0, v[100:101]
	global_store_dword v[0:1], v2, off sc1
	s_waitcnt vmcnt(7)
; __device__ __forceinline__ float bf2f(u16 h) { return __uint_as_float(((unsigned)h) << 16); }
; __device__ __forceinline__ float sigmoidf_(float x) { return 1.f / (1.f + __expf(-x)); }
; template <int EPI>
; __device__ __forceinline__ void gemm_tile(const u16* __restrict__ A, long lda, const u16* __restrict__ Bt, long ldb, int K,
;                                           int brow, int bcol, const Epi& e, u16* shm) {
;     ...
;   for (int mh = 0; mh < 4; ++mh) {
;     float ta[4][2][4], tg[4][2][4];
; #pragma unroll
;     for (int m = mh; m < mh + 1; ++m)
; #pragma unroll
;     for (int n = 0; n < 2; ++n)
; #pragma unroll
;     for (int j = 0; j < 4; ++j) {
;       const int row = brow + ai * HALF + wr * 64 + m * 16 + fq * 4 + j, col = bcol + bj * HALF + wc * 32 + n * 16 + fr;
;       ta[m][n][j] = 0.f; tg[m][n][j] = 0.f;
;       if constexpr (EPI == EPI_RES) ta[m][n][j] = e.res[(long)row * D + col];
;       if constexpr (EPI == EPI_MRG1 || EPI == EPI_MRG2) ta[m][n][j] = e.cf[(long)row * D + col];
;       if constexpr (EPI == EPI_MRG0) tg[m][n][j] = bf2f(e.proj[(long)row * NC + OG + col]);
;       if constexpr (EPI == EPI_MRG1) tg[m][n][j] = bf2f(e.proj[(long)row * NC + OG + 2048 + col]);
;       if constexpr (EPI == EPI_MRG2) tg[m][n][j] = bf2f(e.proj[(long)row * NC + OG + 4096 + col]);
;     }
; #pragma unroll
;     for (int m = mh; m < mh + 1; ++m)
; #pragma unroll
;     for (int n = 0; n < 2; ++n)
; #pragma unroll
;     for (int j = 0; j < 4; ++j) {
;       const int row = brow + ai * HALF + wr * 64 + m * 16 + fq * 4 + j, col = bcol + bj * HALF + wc * 32 + n * 16 + fr;
;       const float v = acc[ai][bj][m][n][j];
;       if constexpr (EPI == EPI_RES) e.cf[(long)row * D + col] = ta[m][n][j] + v;
;       if constexpr (EPI == EPI_MRG0) e.cf[(long)row * D + col] = sigmoidf_(tg[m][n][j]) * v;
;       if constexpr (EPI == EPI_MRG1) e.cf[(long)row * D + col] = ta[m][n][j] + sigmoidf_(tg[m][n][j]) * v;
;       if constexpr (EPI == EPI_MRG2) e.cb[(long)row * D + col] = f2bf(ta[m][n][j] + sigmoidf_(tg[m][n][j]) * v);
;     }
;   }
;   __syncthreads();
	v_add_f32_e32 v2, v35, v75
	v_lshl_add_u64 v[0:1], v[64:65], 0, v[100:101]
	global_store_dword v[0:1], v2, off sc1
	global_load_dword v0, v[66:67], off offset:512
	s_nop 0
	global_load_dword v2, v[82:83], off offset:512
	global_load_dword v32, v[84:85], off offset:512
	global_load_dword v33, v[86:87], off offset:512
	global_load_dword v34, v[66:67], off offset:576
	global_load_dword v35, v[82:83], off offset:576
	global_load_dword v36, v[84:85], off offset:576
	global_load_dword v37, v[86:87], off offset:576
	s_waitcnt vmcnt(7)
	v_add_f32_e32 v28, v28, v0
	v_lshl_add_u64 v[0:1], v[88:89], 0, v[104:105]
	global_store_dword v[0:1], v28, off sc1
	s_waitcnt vmcnt(7)
	v_add_f32_e32 v2, v29, v2
	v_lshl_add_u64 v[0:1], v[62:63], 0, v[104:105]
	global_store_dword v[0:1], v2, off sc1
	s_waitcnt vmcnt(7)
	v_add_f32_e32 v2, v30, v32
	v_lshl_add_u64 v[0:1], v[60:61], 0, v[104:105]
	global_store_dword v[0:1], v2, off sc1
	s_waitcnt vmcnt(7)
	v_add_f32_e32 v2, v31, v33
	v_lshl_add_u64 v[0:1], v[56:57], 0, v[104:105]
	global_store_dword v[0:1], v2, off sc1
	s_waitcnt vmcnt(7)
	v_add_f32_e32 v2, v24, v34
	v_lshl_add_u64 v[0:1], v[88:89], 0, v[100:101]
	global_store_dword v[0:1], v2, off sc1
	s_waitcnt vmcnt(7)
	v_add_f32_e32 v2, v25, v35
	v_lshl_add_u64 v[0:1], v[62:63], 0, v[100:101]
	global_store_dword v[0:1], v2, off sc1
	s_waitcnt vmcnt(7)
	v_add_f32_e32 v2, v26, v36
	v_lshl_add_u64 v[0:1], v[60:61], 0, v[100:101]
	global_store_dword v[0:1], v2, off sc1
	s_waitcnt vmcnt(7)
	v_add_f32_e32 v2, v27, v37
	v_lshl_add_u64 v[0:1], v[56:57], 0, v[100:101]
	global_store_dword v[0:1], v2, off sc1
	global_load_dword v0, v[58:59], off offset:512
	s_nop 0
	global_load_dword v2, v[90:91], off offset:512
	global_load_dword v24, v[92:93], off offset:512
	global_load_dword v25, v[94:95], off offset:512
	global_load_dword v26, v[58:59], off offset:576
	global_load_dword v27, v[90:91], off offset:576
	global_load_dword v28, v[92:93], off offset:576
	global_load_dword v29, v[94:95], off offset:576
	s_waitcnt vmcnt(7)
	v_add_f32_e32 v20, v20, v0
	v_lshl_add_u64 v[0:1], v[96:97], 0, v[104:105]
	global_store_dword v[0:1], v20, off sc1
	s_waitcnt vmcnt(7)
	v_add_f32_e32 v2, v21, v2
	v_lshl_add_u64 v[0:1], v[54:55], 0, v[104:105]
	global_store_dword v[0:1], v2, off sc1
	s_waitcnt vmcnt(7)
	v_add_f32_e32 v2, v22, v24
	v_lshl_add_u64 v[0:1], v[52:53], 0, v[104:105]
	global_store_dword v[0:1], v2, off sc1
	s_waitcnt vmcnt(7)
	v_add_f32_e32 v2, v23, v25
	v_lshl_add_u64 v[0:1], v[48:49], 0, v[104:105]
	global_store_dword v[0:1], v2, off sc1
	s_waitcnt vmcnt(7)
	v_add_f32_e32 v2, v16, v26
	v_lshl_add_u64 v[0:1], v[96:97], 0, v[100:101]
	global_store_dword v[0:1], v2, off sc1
	s_waitcnt vmcnt(7)
	v_add_f32_e32 v2, v17, v27
	v_lshl_add_u64 v[0:1], v[54:55], 0, v[100:101]
	global_store_dword v[0:1], v2, off sc1
	s_waitcnt vmcnt(7)
	v_add_f32_e32 v2, v18, v28
	v_lshl_add_u64 v[0:1], v[52:53], 0, v[100:101]
	global_store_dword v[0:1], v2, off sc1
	s_waitcnt vmcnt(7)
	v_add_f32_e32 v2, v19, v29
	v_lshl_add_u64 v[0:1], v[48:49], 0, v[100:101]
	global_store_dword v[0:1], v2, off sc1
	global_load_dword v0, v[50:51], off offset:512
	s_nop 0
	global_load_dword v2, v[98:99], off offset:512
	global_load_dword v16, v[102:103], off offset:512
	global_load_dword v17, v[106:107], off offset:512
	global_load_dword v18, v[50:51], off offset:576
	global_load_dword v19, v[98:99], off offset:576
	global_load_dword v20, v[102:103], off offset:576
	global_load_dword v21, v[106:107], off offset:576
	s_waitcnt vmcnt(7)
	v_add_f32_e32 v12, v12, v0
	v_lshl_add_u64 v[0:1], v[44:45], 0, v[104:105]
	global_store_dword v[0:1], v12, off sc1
	s_waitcnt vmcnt(7)
	v_add_f32_e32 v2, v13, v2
	v_lshl_add_u64 v[0:1], v[40:41], 0, v[104:105]
	global_store_dword v[0:1], v2, off sc1
	s_waitcnt vmcnt(7)
	v_add_f32_e32 v2, v14, v16
	v_lshl_add_u64 v[0:1], v[46:47], 0, v[104:105]
	global_store_dword v[0:1], v2, off sc1
	s_waitcnt vmcnt(7)
	v_add_f32_e32 v2, v15, v17
	v_lshl_add_u64 v[0:1], v[42:43], 0, v[104:105]
	global_store_dword v[0:1], v2, off sc1
	s_waitcnt vmcnt(7)
	v_add_f32_e32 v2, v8, v18
	v_lshl_add_u64 v[0:1], v[44:45], 0, v[100:101]
	global_store_dword v[0:1], v2, off sc1
	s_waitcnt vmcnt(7)
	v_add_f32_e32 v2, v9, v19
	v_lshl_add_u64 v[0:1], v[40:41], 0, v[100:101]
	global_store_dword v[0:1], v2, off sc1
	s_waitcnt vmcnt(7)
	v_add_f32_e32 v2, v10, v20
	v_lshl_add_u64 v[0:1], v[46:47], 0, v[100:101]
	global_store_dword v[0:1], v2, off sc1
	s_waitcnt vmcnt(7)
	v_add_f32_e32 v2, v11, v21
	v_lshl_add_u64 v[0:1], v[42:43], 0, v[100:101]
	global_store_dword v[0:1], v2, off sc1
	s_barrier
	s_add_i32 s60, s0, s60
	s_cmpk_gt_i32 s60, 0xff
	s_cbranch_scc1 .LBB0_1153

; __device__ __forceinline__ float bf2f(u16 h) { return __uint_as_float(((unsigned)h) << 16); }
; __device__ __forceinline__ float sigmoidf_(float x) { return 1.f / (1.f + __expf(-x)); }
; template <int EPI>
; __device__ __forceinline__ void gemm_tile(const u16* __restrict__ A, long lda, const u16* __restrict__ Bt, long ldb, int K,
;                                           int brow, int bcol, const Epi& e, u16* shm) {
;     ...
;   for (int mh = 0; mh < 4; ++mh) {
;     float ta[4][2][4], tg[4][2][4];
; #pragma unroll
;     for (int m = mh; m < mh + 1; ++m)
; #pragma unroll
;     for (int n = 0; n < 2; ++n)
; #pragma unroll
;     for (int j = 0; j < 4; ++j) {
;       const int row = brow + ai * HALF + wr * 64 + m * 16 + fq * 4 + j, col = bcol + bj * HALF + wc * 32 + n * 16 + fr;
;       ta[m][n][j] = 0.f; tg[m][n][j] = 0.f;
;       if constexpr (EPI == EPI_RES) ta[m][n][j] = e.res[(long)row * D + col];
;       if constexpr (EPI == EPI_MRG1 || EPI == EPI_MRG2) ta[m][n][j] = e.cf[(long)row * D + col];
;       if constexpr (EPI == EPI_MRG0) tg[m][n][j] = bf2f(e.proj[(long)row * NC + OG + col]);
;       if constexpr (EPI == EPI_MRG1) tg[m][n][j] = bf2f(e.proj[(long)row * NC + OG + 2048 + col]);
;       if constexpr (EPI == EPI_MRG2) tg[m][n][j] = bf2f(e.proj[(long)row * NC + OG + 4096 + col]);
;     }
; #pragma unroll
;     for (int m = mh; m < mh + 1; ++m)
; #pragma unroll
;     for (int n = 0; n < 2; ++n)
; #pragma unroll
;     for (int j = 0; j < 4; ++j) {
;       const int row = brow + ai * HALF + wr * 64 + m * 16 + fq * 4 + j, col = bcol + bj * HALF + wc * 32 + n * 16 + fr;
;       const float v = acc[ai][bj][m][n][j];
;       if constexpr (EPI == EPI_RES) e.cf[(long)row * D + col] = ta[m][n][j] + v;
;       if constexpr (EPI == EPI_MRG0) e.cf[(long)row * D + col] = sigmoidf_(tg[m][n][j]) * v;
;       if constexpr (EPI == EPI_MRG1) e.cf[(long)row * D + col] = ta[m][n][j] + sigmoidf_(tg[m][n][j]) * v;
;       if constexpr (EPI == EPI_MRG2) e.cb[(long)row * D + col] = f2bf(ta[m][n][j] + sigmoidf_(tg[m][n][j]) * v);
;     }
.LBB0_1307:
	s_or_b64 exec, exec, s[0:1]
	v_mov_b32_e32 v0, v188
	s_mov_b64 s[0:1], 0x100000
	v_and_b32_e32 v1, 15, v0
	v_ashrrev_i32_e32 v2, 2, v0
	v_lshrrev_b32_e32 v136, 2, v0
	v_lshrrev_b32_e32 v0, 1, v0
	v_and_b32_e32 v2, 0xffffffc0, v2
	v_and_b32_e32 v0, 0x60, v0
	v_lshl_add_u32 v2, s18, 8, v2
	v_or3_b32 v146, v1, v0, s14
	v_and_or_b32 v172, v136, 12, v2
	v_ashrrev_i32_e32 v147, 31, v146
	v_lshlrev_b64 v[0:1], 2, v[146:147]
	v_ashrrev_i32_e32 v173, 31, v172
	v_lshl_add_u64 v[138:139], s[12:13], 0, v[0:1]
	v_lshlrev_b64 v[140:141], 13, v[172:173]
	v_lshl_add_u64 v[136:137], v[138:139], 0, v[140:141]
	global_load_dword v2, v[136:137], off
	v_or_b32_e32 v136, 1, v172
	v_ashrrev_i32_e32 v137, 31, v136
	v_lshlrev_b64 v[144:145], 13, v[136:137]
	v_lshl_add_u64 v[136:137], v[138:139], 0, v[144:145]
	global_load_dword v147, v[136:137], off
	v_or_b32_e32 v136, 2, v172
	v_ashrrev_i32_e32 v137, 31, v136
	v_lshlrev_b64 v[156:157], 13, v[136:137]
	v_lshl_add_u64 v[136:137], v[138:139], 0, v[156:157]
	global_load_dword v160, v[136:137], off
	v_or_b32_e32 v136, 3, v172
	v_ashrrev_i32_e32 v137, 31, v136
	v_lshlrev_b64 v[158:159], 13, v[136:137]
	v_lshl_add_u64 v[136:137], v[138:139], 0, v[158:159]
	global_load_dword v161, v[136:137], off
	v_or_b32_e32 v136, 16, v146
	v_ashrrev_i32_e32 v137, 31, v136
	v_lshl_add_u64 v[154:155], s[12:13], 0, v[140:141]
	v_lshlrev_b64 v[136:137], 2, v[136:137]
	v_lshl_add_u64 v[142:143], v[154:155], 0, v[136:137]
	v_lshl_add_u64 v[148:149], s[12:13], 0, v[144:145]
	global_load_dword v162, v[142:143], off
	v_lshl_add_u64 v[142:143], v[148:149], 0, v[136:137]
	v_lshl_add_u64 v[150:151], s[12:13], 0, v[156:157]
	global_load_dword v163, v[142:143], off
	v_lshl_add_u64 v[142:143], v[150:151], 0, v[136:137]
	v_lshl_add_u64 v[152:153], s[12:13], 0, v[158:159]
	global_load_dword v164, v[142:143], off
	v_lshl_add_u64 v[142:143], v[152:153], 0, v[136:137]
	global_load_dword v165, v[142:143], off
	v_lshl_add_u64 v[0:1], s[4:5], 0, v[0:1]
	v_lshl_add_u64 v[142:143], v[0:1], 0, v[140:141]
	v_readlane_b32 s48, v252, 2
	s_waitcnt vmcnt(0)
	v_add_f32_e32 v2, v132, v2
	global_store_dword v[142:143], v2, off sc1
	v_add_f32_e32 v2, v133, v147
	v_lshl_add_u64 v[132:133], v[0:1], 0, v[144:145]
	global_store_dword v[132:133], v2, off sc1
	v_lshl_add_u64 v[144:145], v[0:1], 0, v[156:157]
	v_add_f32_e32 v2, v134, v160
	global_store_dword v[144:145], v2, off sc1
	v_add_f32_e32 v2, v135, v161
	v_lshl_add_u64 v[134:135], v[0:1], 0, v[158:159]
	global_store_dword v[134:135], v2, off sc1
	v_add_f32_e32 v2, v128, v162
	global_store_dword v[142:143], v2, off offset:64 sc1
	v_or_b32_e32 v128, 16, v172
	v_add_f32_e32 v2, v129, v163
	global_store_dword v[132:133], v2, off offset:64 sc1
	v_ashrrev_i32_e32 v129, 31, v128
	v_add_f32_e32 v2, v130, v164
	global_store_dword v[144:145], v2, off offset:64 sc1
	v_add_f32_e32 v2, v131, v165
	v_lshlrev_b64 v[160:161], 13, v[128:129]
	global_store_dword v[134:135], v2, off offset:64 sc1
	v_lshl_add_u64 v[128:129], v[138:139], 0, v[160:161]
	global_load_dword v2, v[128:129], off
	v_or_b32_e32 v128, 17, v172
	v_ashrrev_i32_e32 v129, 31, v128
	v_lshlrev_b64 v[162:163], 13, v[128:129]
	v_lshl_add_u64 v[128:129], v[138:139], 0, v[162:163]
	global_load_dword v147, v[128:129], off
	v_or_b32_e32 v128, 18, v172
	v_ashrrev_i32_e32 v129, 31, v128
	v_lshlrev_b64 v[164:165], 13, v[128:129]
	v_lshl_add_u64 v[128:129], v[138:139], 0, v[164:165]
	global_load_dword v170, v[128:129], off
	v_or_b32_e32 v128, 19, v172
	v_ashrrev_i32_e32 v129, 31, v128
	v_lshlrev_b64 v[166:167], 13, v[128:129]
	v_lshl_add_u64 v[128:129], v[138:139], 0, v[166:167]
	global_load_dword v171, v[128:129], off
	v_lshl_add_u64 v[128:129], s[12:13], 0, v[160:161]
	v_lshl_add_u64 v[130:131], v[128:129], 0, v[136:137]
	global_load_dword v173, v[130:131], off
	v_lshl_add_u64 v[130:131], s[12:13], 0, v[162:163]
	v_lshl_add_u64 v[156:157], v[130:131], 0, v[136:137]
	global_load_dword v174, v[156:157], off
	v_lshl_add_u64 v[156:157], s[12:13], 0, v[164:165]
	v_lshl_add_u64 v[158:159], v[156:157], 0, v[136:137]
	global_load_dword v175, v[158:159], off
	v_lshl_add_u64 v[158:159], s[12:13], 0, v[166:167]
	v_lshl_add_u64 v[168:169], v[158:159], 0, v[136:137]
	global_load_dword v168, v[168:169], off
	v_lshl_add_u64 v[160:161], v[0:1], 0, v[160:161]
	s_waitcnt vmcnt(7)
	v_add_f32_e32 v2, v124, v2
	global_store_dword v[160:161], v2, off sc1
	s_waitcnt vmcnt(7)
	v_add_f32_e32 v2, v125, v147
	v_lshl_add_u64 v[124:125], v[0:1], 0, v[162:163]
	global_store_dword v[124:125], v2, off sc1
	v_lshl_add_u64 v[162:163], v[0:1], 0, v[164:165]
	s_waitcnt vmcnt(7)
	v_add_f32_e32 v2, v126, v170
	global_store_dword v[162:163], v2, off sc1
	s_waitcnt vmcnt(7)
	v_add_f32_e32 v2, v127, v171
	v_lshl_add_u64 v[126:127], v[0:1], 0, v[166:167]
	global_store_dword v[126:127], v2, off sc1
	s_waitcnt vmcnt(7)
	v_add_f32_e32 v2, v120, v173
	global_store_dword v[160:161], v2, off offset:64 sc1
	v_or_b32_e32 v120, 32, v172
	s_waitcnt vmcnt(7)
	v_add_f32_e32 v2, v121, v174
	global_store_dword v[124:125], v2, off offset:64 sc1
	v_ashrrev_i32_e32 v121, 31, v120
	s_waitcnt vmcnt(7)
	v_add_f32_e32 v2, v122, v175
	global_store_dword v[162:163], v2, off offset:64 sc1
	s_waitcnt vmcnt(7)
; __device__ __forceinline__ float bf2f(u16 h) { return __uint_as_float(((unsigned)h) << 16); }
; __device__ __forceinline__ float sigmoidf_(float x) { return 1.f / (1.f + __expf(-x)); }
; template <int EPI>
; __device__ __forceinline__ void gemm_tile(const u16* __restrict__ A, long lda, const u16* __restrict__ Bt, long ldb, int K,
;                                           int brow, int bcol, const Epi& e, u16* shm) {
;     ...
;   for (int mh = 0; mh < 4; ++mh) {
;     float ta[4][2][4], tg[4][2][4];
; #pragma unroll
;     for (int m = mh; m < mh + 1; ++m)
; #pragma unroll
;     for (int n = 0; n < 2; ++n)
; #pragma unroll
;     for (int j = 0; j < 4; ++j) {
;       const int row = brow + ai * HALF + wr * 64 + m * 16 + fq * 4 + j, col = bcol + bj * HALF + wc * 32 + n * 16 + fr;
;       ta[m][n][j] = 0.f; tg[m][n][j] = 0.f;
;       if constexpr (EPI == EPI_RES) ta[m][n][j] = e.res[(long)row * D + col];
;       if constexpr (EPI == EPI_MRG1 || EPI == EPI_MRG2) ta[m][n][j] = e.cf[(long)row * D + col];
;       if constexpr (EPI == EPI_MRG0) tg[m][n][j] = bf2f(e.proj[(long)row * NC + OG + col]);
;       if constexpr (EPI == EPI_MRG1) tg[m][n][j] = bf2f(e.proj[(long)row * NC + OG + 2048 + col]);
;       if constexpr (EPI == EPI_MRG2) tg[m][n][j] = bf2f(e.proj[(long)row * NC + OG + 4096 + col]);
;     }
; #pragma unroll
;     for (int m = mh; m < mh + 1; ++m)
; #pragma unroll
;     for (int n = 0; n < 2; ++n)
; #pragma unroll
;     for (int j = 0; j < 4; ++j) {
;       const int row = brow + ai * HALF + wr * 64 + m * 16 + fq * 4 + j, col = bcol + bj * HALF + wc * 32 + n * 16 + fr;
;       const float v = acc[ai][bj][m][n][j];
;       if constexpr (EPI == EPI_RES) e.cf[(long)row * D + col] = ta[m][n][j] + v;
;       if constexpr (EPI == EPI_MRG0) e.cf[(long)row * D + col] = sigmoidf_(tg[m][n][j]) * v;
;       if constexpr (EPI == EPI_MRG1) e.cf[(long)row * D + col] = ta[m][n][j] + sigmoidf_(tg[m][n][j]) * v;
;       if constexpr (EPI == EPI_MRG2) e.cb[(long)row * D + col] = f2bf(ta[m][n][j] + sigmoidf_(tg[m][n][j]) * v);
;     }
	v_add_f32_e32 v2, v123, v168
	v_lshlrev_b64 v[168:169], 13, v[120:121]
	global_store_dword v[126:127], v2, off offset:64 sc1
	v_lshl_add_u64 v[120:121], v[138:139], 0, v[168:169]
	global_load_dword v2, v[120:121], off
	v_or_b32_e32 v120, 33, v172
	v_ashrrev_i32_e32 v121, 31, v120
	v_lshlrev_b64 v[170:171], 13, v[120:121]
	v_lshl_add_u64 v[120:121], v[138:139], 0, v[170:171]
	global_load_dword v147, v[120:121], off
	v_or_b32_e32 v120, 34, v172
	v_ashrrev_i32_e32 v121, 31, v120
	v_lshlrev_b64 v[174:175], 13, v[120:121]
	v_lshl_add_u64 v[120:121], v[138:139], 0, v[174:175]
	global_load_dword v173, v[120:121], off
	v_or_b32_e32 v120, 35, v172
	v_ashrrev_i32_e32 v121, 31, v120
	v_lshlrev_b64 v[176:177], 13, v[120:121]
	v_lshl_add_u64 v[120:121], v[138:139], 0, v[176:177]
	global_load_dword v180, v[120:121], off
	v_lshl_add_u64 v[120:121], s[12:13], 0, v[168:169]
	v_lshl_add_u64 v[122:123], v[120:121], 0, v[136:137]
	global_load_dword v181, v[122:123], off
	v_lshl_add_u64 v[122:123], s[12:13], 0, v[170:171]
	v_lshl_add_u64 v[164:165], v[122:123], 0, v[136:137]
	global_load_dword v182, v[164:165], off
	v_lshl_add_u64 v[164:165], s[12:13], 0, v[174:175]
	v_lshl_add_u64 v[166:167], v[164:165], 0, v[136:137]
	global_load_dword v183, v[166:167], off
	v_lshl_add_u64 v[166:167], s[12:13], 0, v[176:177]
	v_lshl_add_u64 v[178:179], v[166:167], 0, v[136:137]
	global_load_dword v178, v[178:179], off
	v_lshl_add_u64 v[168:169], v[0:1], 0, v[168:169]
	s_waitcnt vmcnt(7)
	v_add_f32_e32 v2, v116, v2
	global_store_dword v[168:169], v2, off sc1
	s_waitcnt vmcnt(7)
	v_add_f32_e32 v2, v117, v147
	v_lshl_add_u64 v[116:117], v[0:1], 0, v[170:171]
	global_store_dword v[116:117], v2, off sc1
	v_lshl_add_u64 v[170:171], v[0:1], 0, v[174:175]
	s_waitcnt vmcnt(7)
	v_add_f32_e32 v2, v118, v173
	global_store_dword v[170:171], v2, off sc1
	s_waitcnt vmcnt(7)
	v_add_f32_e32 v2, v119, v180
	v_lshl_add_u64 v[118:119], v[0:1], 0, v[176:177]
	global_store_dword v[118:119], v2, off sc1
	s_waitcnt vmcnt(7)
	v_add_f32_e32 v2, v112, v181
	global_store_dword v[168:169], v2, off offset:64 sc1
	v_or_b32_e32 v112, 48, v172
	s_waitcnt vmcnt(7)
	v_add_f32_e32 v2, v113, v182
	global_store_dword v[116:117], v2, off offset:64 sc1
	v_ashrrev_i32_e32 v113, 31, v112
	s_waitcnt vmcnt(7)
	v_add_f32_e32 v2, v114, v183
	global_store_dword v[170:171], v2, off offset:64 sc1
	v_lshlrev_b64 v[176:177], 13, v[112:113]
	s_waitcnt vmcnt(7)
	v_add_f32_e32 v2, v115, v178
	global_store_dword v[118:119], v2, off offset:64 sc1
	v_lshl_add_u64 v[112:113], v[138:139], 0, v[176:177]
	global_load_dword v2, v[112:113], off
	v_or_b32_e32 v112, 49, v172
	v_ashrrev_i32_e32 v113, 31, v112
	v_lshlrev_b64 v[178:179], 13, v[112:113]
	v_lshl_add_u64 v[112:113], v[138:139], 0, v[178:179]
	global_load_dword v147, v[112:113], off
	v_or_b32_e32 v112, 50, v172
	v_ashrrev_i32_e32 v113, 31, v112
	v_lshlrev_b64 v[180:181], 13, v[112:113]
	v_lshl_add_u64 v[112:113], v[138:139], 0, v[180:181]
	global_load_dword v186, v[112:113], off
	v_or_b32_e32 v112, 51, v172
	v_ashrrev_i32_e32 v113, 31, v112
	v_lshlrev_b64 v[182:183], 13, v[112:113]
	v_lshl_add_u64 v[112:113], v[138:139], 0, v[182:183]
	global_load_dword v187, v[112:113], off
	v_lshl_add_u64 v[112:113], s[12:13], 0, v[176:177]
	v_lshl_add_u64 v[114:115], v[112:113], 0, v[136:137]
	global_load_dword v192, v[114:115], off
	v_lshl_add_u64 v[114:115], s[12:13], 0, v[178:179]
	v_lshl_add_u64 v[172:173], v[114:115], 0, v[136:137]
	global_load_dword v193, v[172:173], off
	v_lshl_add_u64 v[172:173], s[12:13], 0, v[180:181]
	v_lshl_add_u64 v[174:175], v[172:173], 0, v[136:137]
	global_load_dword v194, v[174:175], off
	v_lshl_add_u64 v[174:175], s[12:13], 0, v[182:183]
	v_lshl_add_u64 v[184:185], v[174:175], 0, v[136:137]
	global_load_dword v184, v[184:185], off
	v_lshl_add_u64 v[176:177], v[0:1], 0, v[176:177]
	s_waitcnt vmcnt(7)
	v_add_f32_e32 v2, v108, v2
	global_store_dword v[176:177], v2, off sc1
	s_waitcnt vmcnt(7)
	v_add_f32_e32 v2, v109, v147
	v_lshl_add_u64 v[108:109], v[0:1], 0, v[178:179]
	global_store_dword v[108:109], v2, off sc1
	v_lshl_add_u64 v[178:179], v[0:1], 0, v[180:181]
	s_waitcnt vmcnt(7)
	v_add_f32_e32 v2, v110, v186
	global_store_dword v[178:179], v2, off sc1
	s_waitcnt vmcnt(7)
	v_add_f32_e32 v2, v111, v187
	v_lshl_add_u64 v[110:111], v[0:1], 0, v[182:183]
	global_store_dword v[110:111], v2, off sc1
	s_waitcnt vmcnt(7)
	v_add_f32_e32 v2, v104, v192
	global_store_dword v[176:177], v2, off offset:64 sc1
	v_or_b32_e32 v104, 0x80, v146
	s_waitcnt vmcnt(7)
	v_add_f32_e32 v2, v105, v193
	global_store_dword v[108:109], v2, off offset:64 sc1
	v_ashrrev_i32_e32 v105, 31, v104
	s_waitcnt vmcnt(7)
	v_add_f32_e32 v2, v106, v194
	global_store_dword v[178:179], v2, off offset:64 sc1
	v_lshlrev_b64 v[104:105], 2, v[104:105]
	s_waitcnt vmcnt(7)
	v_add_f32_e32 v2, v107, v184
	global_store_dword v[110:111], v2, off offset:64 sc1
	v_lshl_add_u64 v[106:107], v[154:155], 0, v[104:105]
	global_load_dword v2, v[106:107], off
	v_lshl_add_u64 v[106:107], v[148:149], 0, v[104:105]
	global_load_dword v180, v[106:107], off
	v_lshl_add_u64 v[106:107], v[150:151], 0, v[104:105]
	global_load_dword v181, v[106:107], off
	v_lshl_add_u64 v[106:107], v[152:153], 0, v[104:105]
	global_load_dword v182, v[106:107], off
	v_or_b32_e32 v106, 0x90, v146
	v_ashrrev_i32_e32 v107, 31, v106
	v_lshlrev_b64 v[106:107], 2, v[106:107]
	v_lshl_add_u64 v[146:147], v[154:155], 0, v[106:107]
	global_load_dword v154, v[146:147], off
	v_lshl_add_u64 v[146:147], v[148:149], 0, v[106:107]
	global_load_dword v148, v[146:147], off
	v_lshl_add_u64 v[146:147], v[150:151], 0, v[106:107]
	global_load_dword v149, v[146:147], off
	v_lshl_add_u64 v[146:147], v[152:153], 0, v[106:107]
	global_load_dword v146, v[146:147], off
	s_waitcnt vmcnt(7)
; __device__ __forceinline__ float bf2f(u16 h) { return __uint_as_float(((unsigned)h) << 16); }
; __device__ __forceinline__ float sigmoidf_(float x) { return 1.f / (1.f + __expf(-x)); }
; template <int EPI>
; __device__ __forceinline__ void gemm_tile(const u16* __restrict__ A, long lda, const u16* __restrict__ Bt, long ldb, int K,
;                                           int brow, int bcol, const Epi& e, u16* shm) {
;     ...
;   for (int mh = 0; mh < 4; ++mh) {
;     float ta[4][2][4], tg[4][2][4];
; #pragma unroll
;     for (int m = mh; m < mh + 1; ++m)
; #pragma unroll
;     for (int n = 0; n < 2; ++n)
; #pragma unroll
;     for (int j = 0; j < 4; ++j) {
;       const int row = brow + ai * HALF + wr * 64 + m * 16 + fq * 4 + j, col = bcol + bj * HALF + wc * 32 + n * 16 + fr;
;       ta[m][n][j] = 0.f; tg[m][n][j] = 0.f;
;       if constexpr (EPI == EPI_RES) ta[m][n][j] = e.res[(long)row * D + col];
;       if constexpr (EPI == EPI_MRG1 || EPI == EPI_MRG2) ta[m][n][j] = e.cf[(long)row * D + col];
;       if constexpr (EPI == EPI_MRG0) tg[m][n][j] = bf2f(e.proj[(long)row * NC + OG + col]);
;       if constexpr (EPI == EPI_MRG1) tg[m][n][j] = bf2f(e.proj[(long)row * NC + OG + 2048 + col]);
;       if constexpr (EPI == EPI_MRG2) tg[m][n][j] = bf2f(e.proj[(long)row * NC + OG + 4096 + col]);
;     }
; #pragma unroll
;     for (int m = mh; m < mh + 1; ++m)
; #pragma unroll
;     for (int n = 0; n < 2; ++n)
; #pragma unroll
;     for (int j = 0; j < 4; ++j) {
;       const int row = brow + ai * HALF + wr * 64 + m * 16 + fq * 4 + j, col = bcol + bj * HALF + wc * 32 + n * 16 + fr;
;       const float v = acc[ai][bj][m][n][j];
;       if constexpr (EPI == EPI_RES) e.cf[(long)row * D + col] = ta[m][n][j] + v;
;       if constexpr (EPI == EPI_MRG0) e.cf[(long)row * D + col] = sigmoidf_(tg[m][n][j]) * v;
;       if constexpr (EPI == EPI_MRG1) e.cf[(long)row * D + col] = ta[m][n][j] + sigmoidf_(tg[m][n][j]) * v;
;       if constexpr (EPI == EPI_MRG2) e.cb[(long)row * D + col] = f2bf(ta[m][n][j] + sigmoidf_(tg[m][n][j]) * v);
;     }
	v_add_f32_e32 v2, v100, v2
	global_store_dword v[142:143], v2, off offset:512 sc1
	s_waitcnt vmcnt(7)
	v_add_f32_e32 v2, v101, v180
	global_store_dword v[132:133], v2, off offset:512 sc1
	s_waitcnt vmcnt(7)
	v_add_f32_e32 v2, v102, v181
	global_store_dword v[144:145], v2, off offset:512 sc1
	s_waitcnt vmcnt(7)
	v_add_f32_e32 v2, v103, v182
	global_store_dword v[134:135], v2, off offset:512 sc1
	s_waitcnt vmcnt(7)
	v_add_f32_e32 v2, v96, v154
	global_store_dword v[142:143], v2, off offset:576 sc1
	s_waitcnt vmcnt(7)
	v_add_f32_e32 v2, v97, v148
	global_store_dword v[132:133], v2, off offset:576 sc1
	s_waitcnt vmcnt(7)
	v_add_f32_e32 v2, v98, v149
	global_store_dword v[144:145], v2, off offset:576 sc1
	s_waitcnt vmcnt(7)
	v_add_f32_e32 v2, v99, v146
	global_store_dword v[134:135], v2, off offset:576 sc1
	v_lshl_add_u64 v[96:97], v[128:129], 0, v[104:105]
	global_load_dword v2, v[96:97], off
	v_lshl_add_u64 v[96:97], v[130:131], 0, v[104:105]
	global_load_dword v98, v[96:97], off
	v_lshl_add_u64 v[96:97], v[156:157], 0, v[104:105]
	global_load_dword v99, v[96:97], off
	v_lshl_add_u64 v[96:97], v[158:159], 0, v[104:105]
	global_load_dword v100, v[96:97], off
	v_lshl_add_u64 v[96:97], v[128:129], 0, v[106:107]
	global_load_dword v101, v[96:97], off
	v_lshl_add_u64 v[96:97], v[130:131], 0, v[106:107]
	global_load_dword v102, v[96:97], off
	v_lshl_add_u64 v[96:97], v[156:157], 0, v[106:107]
	global_load_dword v103, v[96:97], off
	v_lshl_add_u64 v[96:97], v[158:159], 0, v[106:107]
	global_load_dword v96, v[96:97], off
	s_waitcnt vmcnt(7)
	v_add_f32_e32 v2, v92, v2
	global_store_dword v[160:161], v2, off offset:512 sc1
	s_waitcnt vmcnt(7)
	v_add_f32_e32 v2, v93, v98
	global_store_dword v[124:125], v2, off offset:512 sc1
	s_waitcnt vmcnt(7)
	v_add_f32_e32 v2, v94, v99
	global_store_dword v[162:163], v2, off offset:512 sc1
	s_waitcnt vmcnt(7)
	v_add_f32_e32 v2, v95, v100
	global_store_dword v[126:127], v2, off offset:512 sc1
	s_waitcnt vmcnt(7)
	v_add_f32_e32 v2, v88, v101
	global_store_dword v[160:161], v2, off offset:576 sc1
	s_waitcnt vmcnt(7)
	v_add_f32_e32 v2, v89, v102
	global_store_dword v[124:125], v2, off offset:576 sc1
	s_waitcnt vmcnt(7)
	v_add_f32_e32 v2, v90, v103
	global_store_dword v[162:163], v2, off offset:576 sc1
	s_waitcnt vmcnt(7)
	v_add_f32_e32 v2, v91, v96
	global_store_dword v[126:127], v2, off offset:576 sc1
	v_lshl_add_u64 v[88:89], v[120:121], 0, v[104:105]
	global_load_dword v2, v[88:89], off
	v_lshl_add_u64 v[88:89], v[122:123], 0, v[104:105]
	global_load_dword v90, v[88:89], off
	v_lshl_add_u64 v[88:89], v[164:165], 0, v[104:105]
	global_load_dword v91, v[88:89], off
	v_lshl_add_u64 v[88:89], v[166:167], 0, v[104:105]
	global_load_dword v92, v[88:89], off
	v_lshl_add_u64 v[88:89], v[120:121], 0, v[106:107]
	global_load_dword v93, v[88:89], off
	v_lshl_add_u64 v[88:89], v[122:123], 0, v[106:107]
	global_load_dword v94, v[88:89], off
	v_lshl_add_u64 v[88:89], v[164:165], 0, v[106:107]
	global_load_dword v95, v[88:89], off
	v_lshl_add_u64 v[88:89], v[166:167], 0, v[106:107]
	global_load_dword v88, v[88:89], off
	s_waitcnt vmcnt(7)
	v_add_f32_e32 v2, v84, v2
	global_store_dword v[168:169], v2, off offset:512 sc1
	s_waitcnt vmcnt(7)
	v_add_f32_e32 v2, v85, v90
	global_store_dword v[116:117], v2, off offset:512 sc1
	s_waitcnt vmcnt(7)
	v_add_f32_e32 v2, v86, v91
	global_store_dword v[170:171], v2, off offset:512 sc1
	s_waitcnt vmcnt(7)
	v_add_f32_e32 v2, v87, v92
	global_store_dword v[118:119], v2, off offset:512 sc1
	s_waitcnt vmcnt(7)
	v_add_f32_e32 v2, v80, v93
	global_store_dword v[168:169], v2, off offset:576 sc1
	s_waitcnt vmcnt(7)
	v_add_f32_e32 v2, v81, v94
	global_store_dword v[116:117], v2, off offset:576 sc1
	s_waitcnt vmcnt(7)
	v_add_f32_e32 v2, v82, v95
	global_store_dword v[170:171], v2, off offset:576 sc1
	s_waitcnt vmcnt(7)
	v_add_f32_e32 v2, v83, v88
	global_store_dword v[118:119], v2, off offset:576 sc1
	v_lshl_add_u64 v[80:81], v[112:113], 0, v[104:105]
	global_load_dword v2, v[80:81], off
	v_lshl_add_u64 v[80:81], v[114:115], 0, v[104:105]
	global_load_dword v82, v[80:81], off
	v_lshl_add_u64 v[80:81], v[172:173], 0, v[104:105]
	global_load_dword v83, v[80:81], off
	v_lshl_add_u64 v[80:81], v[174:175], 0, v[104:105]
	global_load_dword v84, v[80:81], off
	v_lshl_add_u64 v[80:81], v[112:113], 0, v[106:107]
	global_load_dword v85, v[80:81], off
	v_lshl_add_u64 v[80:81], v[114:115], 0, v[106:107]
	global_load_dword v86, v[80:81], off
	v_lshl_add_u64 v[80:81], v[172:173], 0, v[106:107]
	global_load_dword v87, v[80:81], off
	v_lshl_add_u64 v[80:81], v[174:175], 0, v[106:107]
	global_load_dword v80, v[80:81], off
	s_waitcnt vmcnt(7)
	v_add_f32_e32 v2, v76, v2
	global_store_dword v[176:177], v2, off offset:512 sc1
	s_waitcnt vmcnt(7)
	v_add_f32_e32 v2, v77, v82
	global_store_dword v[108:109], v2, off offset:512 sc1
	s_waitcnt vmcnt(7)
	v_add_f32_e32 v2, v78, v83
	global_store_dword v[178:179], v2, off offset:512 sc1
	s_waitcnt vmcnt(7)
	v_add_f32_e32 v2, v79, v84
	global_store_dword v[110:111], v2, off offset:512 sc1
	s_waitcnt vmcnt(7)
	v_add_f32_e32 v2, v72, v85
	global_store_dword v[176:177], v2, off offset:576 sc1
	s_waitcnt vmcnt(7)
	v_add_f32_e32 v2, v73, v86
	global_store_dword v[108:109], v2, off offset:576 sc1
	s_waitcnt vmcnt(7)
	v_add_f32_e32 v2, v74, v87
	global_store_dword v[178:179], v2, off offset:576 sc1
	s_waitcnt vmcnt(7)
; __device__ __forceinline__ float bf2f(u16 h) { return __uint_as_float(((unsigned)h) << 16); }
; __device__ __forceinline__ float sigmoidf_(float x) { return 1.f / (1.f + __expf(-x)); }
; template <int EPI>
; __device__ __forceinline__ void gemm_tile(const u16* __restrict__ A, long lda, const u16* __restrict__ Bt, long ldb, int K,
;                                           int brow, int bcol, const Epi& e, u16* shm) {
;     ...
;   for (int mh = 0; mh < 4; ++mh) {
;     float ta[4][2][4], tg[4][2][4];
; #pragma unroll
;     for (int m = mh; m < mh + 1; ++m)
; #pragma unroll
;     for (int n = 0; n < 2; ++n)
; #pragma unroll
;     for (int j = 0; j < 4; ++j) {
;       const int row = brow + ai * HALF + wr * 64 + m * 16 + fq * 4 + j, col = bcol + bj * HALF + wc * 32 + n * 16 + fr;
;       ta[m][n][j] = 0.f; tg[m][n][j] = 0.f;
;       if constexpr (EPI == EPI_RES) ta[m][n][j] = e.res[(long)row * D + col];
;       if constexpr (EPI == EPI_MRG1 || EPI == EPI_MRG2) ta[m][n][j] = e.cf[(long)row * D + col];
;       if constexpr (EPI == EPI_MRG0) tg[m][n][j] = bf2f(e.proj[(long)row * NC + OG + col]);
;       if constexpr (EPI == EPI_MRG1) tg[m][n][j] = bf2f(e.proj[(long)row * NC + OG + 2048 + col]);
;       if constexpr (EPI == EPI_MRG2) tg[m][n][j] = bf2f(e.proj[(long)row * NC + OG + 4096 + col]);
;     }
; #pragma unroll
;     for (int m = mh; m < mh + 1; ++m)
; #pragma unroll
;     for (int n = 0; n < 2; ++n)
; #pragma unroll
;     for (int j = 0; j < 4; ++j) {
;       const int row = brow + ai * HALF + wr * 64 + m * 16 + fq * 4 + j, col = bcol + bj * HALF + wc * 32 + n * 16 + fr;
;       const float v = acc[ai][bj][m][n][j];
;       if constexpr (EPI == EPI_RES) e.cf[(long)row * D + col] = ta[m][n][j] + v;
;       if constexpr (EPI == EPI_MRG0) e.cf[(long)row * D + col] = sigmoidf_(tg[m][n][j]) * v;
;       if constexpr (EPI == EPI_MRG1) e.cf[(long)row * D + col] = ta[m][n][j] + sigmoidf_(tg[m][n][j]) * v;
;       if constexpr (EPI == EPI_MRG2) e.cb[(long)row * D + col] = f2bf(ta[m][n][j] + sigmoidf_(tg[m][n][j]) * v);
;     }
	v_add_f32_e32 v2, v75, v80
	v_lshl_add_u64 v[80:81], v[140:141], 0, s[0:1]
	s_mov_b64 s[0:1], 0x102000
	global_store_dword v[110:111], v2, off offset:576 sc1
	v_lshl_add_u64 v[72:73], v[138:139], 0, v[80:81]
	v_lshl_add_u64 v[82:83], v[140:141], 0, s[0:1]
	s_mov_b64 s[0:1], 0x104000
	global_load_dword v2, v[72:73], off
	v_lshl_add_u64 v[72:73], v[138:139], 0, v[82:83]
	v_lshl_add_u64 v[84:85], v[140:141], 0, s[0:1]
	s_mov_b64 s[0:1], 0x106000
	global_load_dword v90, v[72:73], off
	v_lshl_add_u64 v[72:73], v[138:139], 0, v[84:85]
	v_lshl_add_u64 v[86:87], v[140:141], 0, s[0:1]
	global_load_dword v91, v[72:73], off
	v_lshl_add_u64 v[72:73], v[138:139], 0, v[86:87]
	global_load_dword v92, v[72:73], off
	v_lshl_add_u64 v[72:73], s[12:13], 0, v[80:81]
	v_lshl_add_u64 v[74:75], v[72:73], 0, v[136:137]
	global_load_dword v93, v[74:75], off
	v_lshl_add_u64 v[74:75], s[12:13], 0, v[82:83]
	v_lshl_add_u64 v[76:77], v[74:75], 0, v[136:137]
	global_load_dword v94, v[76:77], off
	v_lshl_add_u64 v[76:77], s[12:13], 0, v[84:85]
	v_lshl_add_u64 v[78:79], v[76:77], 0, v[136:137]
	global_load_dword v95, v[78:79], off
	v_lshl_add_u64 v[78:79], s[12:13], 0, v[86:87]
	v_lshl_add_u64 v[88:89], v[78:79], 0, v[136:137]
	global_load_dword v88, v[88:89], off
	v_lshl_add_u64 v[80:81], v[0:1], 0, v[80:81]
	s_mov_b64 s[0:1], 0x120000
	s_waitcnt vmcnt(7)
	v_add_f32_e32 v2, v68, v2
	global_store_dword v[80:81], v2, off sc1
	s_waitcnt vmcnt(7)
	v_add_f32_e32 v2, v69, v90
	v_lshl_add_u64 v[68:69], v[0:1], 0, v[82:83]
	global_store_dword v[68:69], v2, off sc1
	s_waitcnt vmcnt(7)
	v_add_f32_e32 v2, v70, v91
	v_lshl_add_u64 v[82:83], v[0:1], 0, v[84:85]
	global_store_dword v[82:83], v2, off sc1
	s_waitcnt vmcnt(7)
	v_add_f32_e32 v2, v71, v92
	v_lshl_add_u64 v[70:71], v[0:1], 0, v[86:87]
	global_store_dword v[70:71], v2, off sc1
	s_waitcnt vmcnt(7)
	v_add_f32_e32 v2, v64, v93
	global_store_dword v[80:81], v2, off offset:64 sc1
	s_waitcnt vmcnt(7)
	v_add_f32_e32 v2, v65, v94
	global_store_dword v[68:69], v2, off offset:64 sc1
	s_waitcnt vmcnt(7)
	v_add_f32_e32 v2, v66, v95
	global_store_dword v[82:83], v2, off offset:64 sc1
	s_waitcnt vmcnt(7)
	v_add_f32_e32 v2, v67, v88
	v_lshl_add_u64 v[88:89], v[140:141], 0, s[0:1]
	s_mov_b64 s[0:1], 0x122000
	global_store_dword v[70:71], v2, off offset:64 sc1
	v_lshl_add_u64 v[64:65], v[138:139], 0, v[88:89]
	v_lshl_add_u64 v[90:91], v[140:141], 0, s[0:1]
	s_mov_b64 s[0:1], 0x124000
	global_load_dword v2, v[64:65], off
	v_lshl_add_u64 v[64:65], v[138:139], 0, v[90:91]
	v_lshl_add_u64 v[92:93], v[140:141], 0, s[0:1]
	s_mov_b64 s[0:1], 0x126000
	global_load_dword v98, v[64:65], off
	v_lshl_add_u64 v[64:65], v[138:139], 0, v[92:93]
	v_lshl_add_u64 v[94:95], v[140:141], 0, s[0:1]
	global_load_dword v99, v[64:65], off
	v_lshl_add_u64 v[64:65], v[138:139], 0, v[94:95]
	global_load_dword v100, v[64:65], off
	v_lshl_add_u64 v[64:65], s[12:13], 0, v[88:89]
	v_lshl_add_u64 v[66:67], v[64:65], 0, v[136:137]
	global_load_dword v101, v[66:67], off
	v_lshl_add_u64 v[66:67], s[12:13], 0, v[90:91]
	v_lshl_add_u64 v[84:85], v[66:67], 0, v[136:137]
	global_load_dword v102, v[84:85], off
	v_lshl_add_u64 v[84:85], s[12:13], 0, v[92:93]
	v_lshl_add_u64 v[86:87], v[84:85], 0, v[136:137]
	global_load_dword v103, v[86:87], off
	v_lshl_add_u64 v[86:87], s[12:13], 0, v[94:95]
	v_lshl_add_u64 v[96:97], v[86:87], 0, v[136:137]
	global_load_dword v96, v[96:97], off
	v_lshl_add_u64 v[88:89], v[0:1], 0, v[88:89]
	s_mov_b64 s[0:1], 0x140000
	s_waitcnt vmcnt(7)
	v_add_f32_e32 v2, v60, v2
	global_store_dword v[88:89], v2, off sc1
	s_waitcnt vmcnt(7)
	v_add_f32_e32 v2, v61, v98
	v_lshl_add_u64 v[60:61], v[0:1], 0, v[90:91]
	global_store_dword v[60:61], v2, off sc1
	s_waitcnt vmcnt(7)
	v_add_f32_e32 v2, v62, v99
	v_lshl_add_u64 v[90:91], v[0:1], 0, v[92:93]
	global_store_dword v[90:91], v2, off sc1
	s_waitcnt vmcnt(7)
	v_add_f32_e32 v2, v63, v100
	v_lshl_add_u64 v[62:63], v[0:1], 0, v[94:95]
	global_store_dword v[62:63], v2, off sc1
	s_waitcnt vmcnt(7)
	v_add_f32_e32 v2, v56, v101
	global_store_dword v[88:89], v2, off offset:64 sc1
	s_waitcnt vmcnt(7)
	v_add_f32_e32 v2, v57, v102
	global_store_dword v[60:61], v2, off offset:64 sc1
	s_waitcnt vmcnt(7)
	v_add_f32_e32 v2, v58, v103
	global_store_dword v[90:91], v2, off offset:64 sc1
	s_waitcnt vmcnt(7)
	v_add_f32_e32 v2, v59, v96
	v_lshl_add_u64 v[96:97], v[140:141], 0, s[0:1]
	s_mov_b64 s[0:1], 0x142000
	global_store_dword v[62:63], v2, off offset:64 sc1
	v_lshl_add_u64 v[56:57], v[138:139], 0, v[96:97]
	v_lshl_add_u64 v[98:99], v[140:141], 0, s[0:1]
	s_mov_b64 s[0:1], 0x144000
	global_load_dword v2, v[56:57], off
	v_lshl_add_u64 v[56:57], v[138:139], 0, v[98:99]
	v_lshl_add_u64 v[100:101], v[140:141], 0, s[0:1]
	s_mov_b64 s[0:1], 0x146000
	global_load_dword v110, v[56:57], off
	v_lshl_add_u64 v[56:57], v[138:139], 0, v[100:101]
	v_lshl_add_u64 v[102:103], v[140:141], 0, s[0:1]
	global_load_dword v111, v[56:57], off
	v_lshl_add_u64 v[56:57], v[138:139], 0, v[102:103]
	global_load_dword v112, v[56:57], off
	v_lshl_add_u64 v[56:57], s[12:13], 0, v[96:97]
	v_lshl_add_u64 v[58:59], v[56:57], 0, v[136:137]
	global_load_dword v113, v[58:59], off
	v_lshl_add_u64 v[58:59], s[12:13], 0, v[98:99]
	v_lshl_add_u64 v[92:93], v[58:59], 0, v[136:137]
	global_load_dword v114, v[92:93], off
	v_lshl_add_u64 v[92:93], s[12:13], 0, v[100:101]
	v_lshl_add_u64 v[94:95], v[92:93], 0, v[136:137]
	global_load_dword v115, v[94:95], off
	v_lshl_add_u64 v[94:95], s[12:13], 0, v[102:103]
	v_lshl_add_u64 v[108:109], v[94:95], 0, v[136:137]
	global_load_dword v108, v[108:109], off
	v_lshl_add_u64 v[96:97], v[0:1], 0, v[96:97]
	s_mov_b64 s[0:1], 0x160000
	s_waitcnt vmcnt(7)
; __device__ __forceinline__ float sigmoidf_(float x) { return 1.f / (1.f + __expf(-x)); }
; template <int EPI>
; __device__ __forceinline__ void gemm_tile(const u16* __restrict__ A, long lda, const u16* __restrict__ Bt, long ldb, int K,
;                                           int brow, int bcol, const Epi& e, u16* shm) {
;     ...
; #pragma unroll
;     for (int m = mh; m < mh + 1; ++m)
; #pragma unroll
;     for (int n = 0; n < 2; ++n)
; #pragma unroll
;     for (int j = 0; j < 4; ++j) {
;       const int row = brow + ai * HALF + wr * 64 + m * 16 + fq * 4 + j, col = bcol + bj * HALF + wc * 32 + n * 16 + fr;
;       const float v = acc[ai][bj][m][n][j];
;       if constexpr (EPI == EPI_RES) e.cf[(long)row * D + col] = ta[m][n][j] + v;
;       if constexpr (EPI == EPI_MRG0) e.cf[(long)row * D + col] = sigmoidf_(tg[m][n][j]) * v;
;       if constexpr (EPI == EPI_MRG1) e.cf[(long)row * D + col] = ta[m][n][j] + sigmoidf_(tg[m][n][j]) * v;
;       if constexpr (EPI == EPI_MRG2) e.cb[(long)row * D + col] = f2bf(ta[m][n][j] + sigmoidf_(tg[m][n][j]) * v);
;     }
	v_add_f32_e32 v2, v52, v2
	global_store_dword v[96:97], v2, off sc1
	s_waitcnt vmcnt(7)
	v_add_f32_e32 v2, v53, v110
	v_lshl_add_u64 v[52:53], v[0:1], 0, v[98:99]
	global_store_dword v[52:53], v2, off sc1
	s_waitcnt vmcnt(7)
	v_add_f32_e32 v2, v54, v111
	v_lshl_add_u64 v[98:99], v[0:1], 0, v[100:101]
	global_store_dword v[98:99], v2, off sc1
	s_waitcnt vmcnt(7)
	v_add_f32_e32 v2, v55, v112
	v_lshl_add_u64 v[54:55], v[0:1], 0, v[102:103]
	global_store_dword v[54:55], v2, off sc1
	s_waitcnt vmcnt(7)
	v_add_f32_e32 v2, v48, v113
	global_store_dword v[96:97], v2, off offset:64 sc1
	s_waitcnt vmcnt(7)
	v_add_f32_e32 v2, v49, v114
	global_store_dword v[52:53], v2, off offset:64 sc1
	s_waitcnt vmcnt(7)
	v_add_f32_e32 v2, v50, v115
	global_store_dword v[98:99], v2, off offset:64 sc1
	s_waitcnt vmcnt(7)
	v_add_f32_e32 v2, v51, v108
	v_lshl_add_u64 v[108:109], v[140:141], 0, s[0:1]
	s_mov_b64 s[0:1], 0x162000
	global_store_dword v[54:55], v2, off offset:64 sc1
	v_lshl_add_u64 v[48:49], v[138:139], 0, v[108:109]
	v_lshl_add_u64 v[110:111], v[140:141], 0, s[0:1]
	s_mov_b64 s[0:1], 0x164000
	global_load_dword v2, v[48:49], off
	v_lshl_add_u64 v[48:49], v[138:139], 0, v[110:111]
	v_lshl_add_u64 v[112:113], v[140:141], 0, s[0:1]
	s_mov_b64 s[0:1], 0x166000
	global_load_dword v118, v[48:49], off
	v_lshl_add_u64 v[48:49], v[138:139], 0, v[112:113]
	v_lshl_add_u64 v[114:115], v[140:141], 0, s[0:1]
	global_load_dword v119, v[48:49], off
	v_lshl_add_u64 v[48:49], v[138:139], 0, v[114:115]
	global_load_dword v120, v[48:49], off
	v_lshl_add_u64 v[48:49], s[12:13], 0, v[108:109]
	v_lshl_add_u64 v[50:51], v[48:49], 0, v[136:137]
	global_load_dword v121, v[50:51], off
	v_lshl_add_u64 v[50:51], s[12:13], 0, v[110:111]
	v_lshl_add_u64 v[100:101], v[50:51], 0, v[136:137]
	global_load_dword v122, v[100:101], off
	v_lshl_add_u64 v[100:101], s[12:13], 0, v[112:113]
	v_lshl_add_u64 v[102:103], v[100:101], 0, v[136:137]
	global_load_dword v123, v[102:103], off
	v_lshl_add_u64 v[102:103], s[12:13], 0, v[114:115]
	v_lshl_add_u64 v[116:117], v[102:103], 0, v[136:137]
	global_load_dword v116, v[116:117], off
	v_lshl_add_u64 v[108:109], v[0:1], 0, v[108:109]
	s_mov_b32 s0, s48
	s_waitcnt vmcnt(7)
	v_add_f32_e32 v2, v44, v2
	global_store_dword v[108:109], v2, off sc1
	s_waitcnt vmcnt(7)
	v_add_f32_e32 v2, v45, v118
	v_lshl_add_u64 v[44:45], v[0:1], 0, v[110:111]
	global_store_dword v[44:45], v2, off sc1
	s_waitcnt vmcnt(7)
	v_add_f32_e32 v2, v46, v119
	v_lshl_add_u64 v[110:111], v[0:1], 0, v[112:113]
	global_store_dword v[110:111], v2, off sc1
	s_waitcnt vmcnt(7)
	v_add_f32_e32 v2, v47, v120
	v_lshl_add_u64 v[0:1], v[0:1], 0, v[114:115]
	global_store_dword v[0:1], v2, off sc1
	s_waitcnt vmcnt(7)
	v_add_f32_e32 v2, v40, v121
	global_store_dword v[108:109], v2, off offset:64 sc1
	s_waitcnt vmcnt(7)
	v_add_f32_e32 v2, v41, v122
	global_store_dword v[44:45], v2, off offset:64 sc1
	v_lshl_add_u64 v[40:41], v[72:73], 0, v[104:105]
	s_waitcnt vmcnt(7)
	v_add_f32_e32 v2, v42, v123
	global_store_dword v[110:111], v2, off offset:64 sc1
	s_waitcnt vmcnt(7)
	v_add_f32_e32 v2, v43, v116
	global_store_dword v[0:1], v2, off offset:64 sc1
	global_load_dword v2, v[40:41], off
	v_lshl_add_u64 v[40:41], v[74:75], 0, v[104:105]
	global_load_dword v42, v[40:41], off
	v_lshl_add_u64 v[40:41], v[76:77], 0, v[104:105]
	global_load_dword v43, v[40:41], off
	v_lshl_add_u64 v[40:41], v[78:79], 0, v[104:105]
	global_load_dword v46, v[40:41], off
	v_lshl_add_u64 v[40:41], v[72:73], 0, v[106:107]
	global_load_dword v47, v[40:41], off
	v_lshl_add_u64 v[40:41], v[74:75], 0, v[106:107]
	global_load_dword v72, v[40:41], off
	v_lshl_add_u64 v[40:41], v[76:77], 0, v[106:107]
	global_load_dword v73, v[40:41], off
	v_lshl_add_u64 v[40:41], v[78:79], 0, v[106:107]
	global_load_dword v40, v[40:41], off
	s_waitcnt vmcnt(7)
	v_add_f32_e32 v2, v36, v2
	global_store_dword v[80:81], v2, off offset:512 sc1
	s_waitcnt vmcnt(7)
	v_add_f32_e32 v2, v37, v42
	global_store_dword v[68:69], v2, off offset:512 sc1
	s_waitcnt vmcnt(7)
	v_add_f32_e32 v2, v38, v43
	global_store_dword v[82:83], v2, off offset:512 sc1
	s_waitcnt vmcnt(7)
	v_add_f32_e32 v2, v39, v46
	global_store_dword v[70:71], v2, off offset:512 sc1
	s_waitcnt vmcnt(7)
	v_add_f32_e32 v2, v32, v47
	global_store_dword v[80:81], v2, off offset:576 sc1
	s_waitcnt vmcnt(7)
	v_add_f32_e32 v2, v33, v72
	global_store_dword v[68:69], v2, off offset:576 sc1
	s_waitcnt vmcnt(7)
	v_add_f32_e32 v2, v34, v73
	global_store_dword v[82:83], v2, off offset:576 sc1
	s_waitcnt vmcnt(7)
; __device__ __forceinline__ float sigmoidf_(float x) { return 1.f / (1.f + __expf(-x)); }
; template <int EPI>
; __device__ __forceinline__ void gemm_tile(const u16* __restrict__ A, long lda, const u16* __restrict__ Bt, long ldb, int K,
;                                           int brow, int bcol, const Epi& e, u16* shm) {
;     ...
; #pragma unroll
;     for (int m = mh; m < mh + 1; ++m)
; #pragma unroll
;     for (int n = 0; n < 2; ++n)
; #pragma unroll
;     for (int j = 0; j < 4; ++j) {
;       const int row = brow + ai * HALF + wr * 64 + m * 16 + fq * 4 + j, col = bcol + bj * HALF + wc * 32 + n * 16 + fr;
;       const float v = acc[ai][bj][m][n][j];
;       if constexpr (EPI == EPI_RES) e.cf[(long)row * D + col] = ta[m][n][j] + v;
;       if constexpr (EPI == EPI_MRG0) e.cf[(long)row * D + col] = sigmoidf_(tg[m][n][j]) * v;
;       if constexpr (EPI == EPI_MRG1) e.cf[(long)row * D + col] = ta[m][n][j] + sigmoidf_(tg[m][n][j]) * v;
;       if constexpr (EPI == EPI_MRG2) e.cb[(long)row * D + col] = f2bf(ta[m][n][j] + sigmoidf_(tg[m][n][j]) * v);
;     }
	v_add_f32_e32 v2, v35, v40
	global_store_dword v[70:71], v2, off offset:576 sc1
	v_lshl_add_u64 v[32:33], v[64:65], 0, v[104:105]
	global_load_dword v2, v[32:33], off
	v_lshl_add_u64 v[32:33], v[66:67], 0, v[104:105]
	global_load_dword v34, v[32:33], off
	v_lshl_add_u64 v[32:33], v[84:85], 0, v[104:105]
	global_load_dword v35, v[32:33], off
	v_lshl_add_u64 v[32:33], v[86:87], 0, v[104:105]
	global_load_dword v36, v[32:33], off
	v_lshl_add_u64 v[32:33], v[64:65], 0, v[106:107]
	global_load_dword v37, v[32:33], off
	v_lshl_add_u64 v[32:33], v[66:67], 0, v[106:107]
	global_load_dword v38, v[32:33], off
	v_lshl_add_u64 v[32:33], v[84:85], 0, v[106:107]
	global_load_dword v39, v[32:33], off
	v_lshl_add_u64 v[32:33], v[86:87], 0, v[106:107]
	global_load_dword v32, v[32:33], off
	s_waitcnt vmcnt(7)
	v_add_f32_e32 v2, v28, v2
	global_store_dword v[88:89], v2, off offset:512 sc1
	s_waitcnt vmcnt(7)
	v_add_f32_e32 v2, v29, v34
	global_store_dword v[60:61], v2, off offset:512 sc1
	s_waitcnt vmcnt(7)
	v_add_f32_e32 v2, v30, v35
	global_store_dword v[90:91], v2, off offset:512 sc1
	s_waitcnt vmcnt(7)
	v_add_f32_e32 v2, v31, v36
	global_store_dword v[62:63], v2, off offset:512 sc1
	s_waitcnt vmcnt(7)
	v_add_f32_e32 v2, v24, v37
	global_store_dword v[88:89], v2, off offset:576 sc1
	s_waitcnt vmcnt(7)
	v_add_f32_e32 v2, v25, v38
	global_store_dword v[60:61], v2, off offset:576 sc1
	s_waitcnt vmcnt(7)
	v_add_f32_e32 v2, v26, v39
	global_store_dword v[90:91], v2, off offset:576 sc1
	s_waitcnt vmcnt(7)
	v_add_f32_e32 v2, v27, v32
	global_store_dword v[62:63], v2, off offset:576 sc1
	v_lshl_add_u64 v[24:25], v[56:57], 0, v[104:105]
	global_load_dword v2, v[24:25], off
	v_lshl_add_u64 v[24:25], v[58:59], 0, v[104:105]
	global_load_dword v26, v[24:25], off
	v_lshl_add_u64 v[24:25], v[92:93], 0, v[104:105]
	global_load_dword v27, v[24:25], off
	v_lshl_add_u64 v[24:25], v[94:95], 0, v[104:105]
	global_load_dword v28, v[24:25], off
	v_lshl_add_u64 v[24:25], v[56:57], 0, v[106:107]
	global_load_dword v29, v[24:25], off
	v_lshl_add_u64 v[24:25], v[58:59], 0, v[106:107]
	global_load_dword v30, v[24:25], off
	v_lshl_add_u64 v[24:25], v[92:93], 0, v[106:107]
	global_load_dword v31, v[24:25], off
	v_lshl_add_u64 v[24:25], v[94:95], 0, v[106:107]
	global_load_dword v24, v[24:25], off
	s_waitcnt vmcnt(7)
	v_add_f32_e32 v2, v20, v2
	global_store_dword v[96:97], v2, off offset:512 sc1
	s_waitcnt vmcnt(7)
	v_add_f32_e32 v2, v21, v26
	global_store_dword v[52:53], v2, off offset:512 sc1
	s_waitcnt vmcnt(7)
	v_add_f32_e32 v2, v22, v27
	global_store_dword v[98:99], v2, off offset:512 sc1
	s_waitcnt vmcnt(7)
	v_add_f32_e32 v2, v23, v28
	global_store_dword v[54:55], v2, off offset:512 sc1
	s_waitcnt vmcnt(7)
	v_add_f32_e32 v2, v16, v29
	global_store_dword v[96:97], v2, off offset:576 sc1
	s_waitcnt vmcnt(7)
	v_add_f32_e32 v2, v17, v30
	global_store_dword v[52:53], v2, off offset:576 sc1
	s_waitcnt vmcnt(7)
	v_add_f32_e32 v2, v18, v31
	global_store_dword v[98:99], v2, off offset:576 sc1
	s_waitcnt vmcnt(7)
	v_add_f32_e32 v2, v19, v24
	global_store_dword v[54:55], v2, off offset:576 sc1
	v_lshl_add_u64 v[16:17], v[48:49], 0, v[104:105]
	global_load_dword v2, v[16:17], off
	v_lshl_add_u64 v[16:17], v[50:51], 0, v[104:105]
	global_load_dword v18, v[16:17], off
	v_lshl_add_u64 v[16:17], v[100:101], 0, v[104:105]
	global_load_dword v19, v[16:17], off
	v_lshl_add_u64 v[16:17], v[102:103], 0, v[104:105]
	global_load_dword v20, v[16:17], off
	v_lshl_add_u64 v[16:17], v[48:49], 0, v[106:107]
	global_load_dword v21, v[16:17], off
	v_lshl_add_u64 v[16:17], v[50:51], 0, v[106:107]
	global_load_dword v22, v[16:17], off
	v_lshl_add_u64 v[16:17], v[100:101], 0, v[106:107]
	global_load_dword v23, v[16:17], off
	v_lshl_add_u64 v[16:17], v[102:103], 0, v[106:107]
	global_load_dword v16, v[16:17], off
	s_waitcnt vmcnt(7)
	v_add_f32_e32 v2, v12, v2
	global_store_dword v[108:109], v2, off offset:512 sc1
	s_waitcnt vmcnt(7)
	v_add_f32_e32 v2, v13, v18
	global_store_dword v[44:45], v2, off offset:512 sc1
	s_waitcnt vmcnt(7)
	v_add_f32_e32 v2, v14, v19
	global_store_dword v[110:111], v2, off offset:512 sc1
	s_waitcnt vmcnt(7)
	v_add_f32_e32 v2, v15, v20
	global_store_dword v[0:1], v2, off offset:512 sc1
	s_waitcnt vmcnt(7)
	v_add_f32_e32 v2, v8, v21
	global_store_dword v[108:109], v2, off offset:576 sc1
	s_waitcnt vmcnt(7)
	v_add_f32_e32 v2, v9, v22
	global_store_dword v[44:45], v2, off offset:576 sc1
	s_waitcnt vmcnt(7)
	v_add_f32_e32 v2, v10, v23
	global_store_dword v[110:111], v2, off offset:576 sc1
	s_waitcnt vmcnt(7)
	v_add_f32_e32 v2, v11, v16
	global_store_dword v[0:1], v2, off offset:576 sc1
	s_barrier
	s_add_i32 s60, s0, s60
	s_cmpk_gt_i32 s60, 0xff
	s_cbranch_scc1 .LBB0_1314
